# poolconv (A2) and sgu (A3) output stores with sc1 nt (consumed by another XCD's GEMM), test on top of v70
# baseline (speedup 1.0000x reference)
; __device__ __forceinline__ f32x2 bf2x2(unsigned w) { return (f32x2){__builtin_bit_cast(float, w << 16), __builtin_bit_cast(float, w & 0xffff0000u)}; }
; #define PC_POOL(WIN) do { _Pragma("unroll") for (int t = 0; t < 8; ++t) { const f32x2 ut = bf2x2(uraw[15 + t]); f32x2 s = ut; _Pragma("unroll") for (int j = 1; j < WIN; ++j) s += bf2x2(uraw[15 + t - j]); \
;         const int cnt = min(ts + t + 1, WIN); const f32x2 p = s * __builtin_amdgcn_rcpf((float)cnt) - ut; *(unsigned*)(A2 + (size_t)(mt + t) * 1024 + c0) = pk2(p.x, p.y); } } while (0)
; __device__ __forceinline__ void pc_pass(int Q, const bf16* UG, bf16* A2, const float* cw, const float* cbias, LAS float* Yw, int mt, int ts, int lane) {
;     ...
;     if (Q == 0) PC_POOL(2); else if (Q == 1) PC_POOL(4); else if (Q == 2) PC_POOL(8); else PC_POOL(16);
;     ...
;     f32x2 y[8];
; #pragma unroll
;     for (int t = 0; t < 8; ++t) y[t] = cb;
; #pragma unroll
;     for (int i = 0; i < 38; ++i) { const f32x2 gv = bf2x2(graw[i]);
; #pragma unroll
;         for (int t = 0; t < 8; ++t) if (i - t >= 0 && i - t < 31) y[t] = __builtin_elementwise_fma(w[i - t], gv, y[t]); }
.LBB0_140:
	s_waitcnt vmcnt(38)
	v_lshlrev_b32_e32 v190, 16, v191
	v_and_b32_e32 v191, 0xffff0000, v191
	s_waitcnt vmcnt(37)
	v_lshlrev_b32_e32 v188, 16, v189
	v_and_b32_e32 v189, 0xffff0000, v189
	s_waitcnt vmcnt(0)
	v_pk_fma_f32 v[226:227], v[68:69], v[190:191], v[118:119]
	v_lshlrev_b32_e32 v186, 16, v187
	v_and_b32_e32 v187, 0xffff0000, v187
	v_pk_fma_f32 v[226:227], v[70:71], v[188:189], v[226:227]
	v_lshlrev_b32_e32 v184, 16, v185
	v_and_b32_e32 v185, 0xffff0000, v185
	v_pk_fma_f32 v[226:227], v[60:61], v[186:187], v[226:227]
	v_lshlrev_b32_e32 v182, 16, v183
	v_and_b32_e32 v183, 0xffff0000, v183
	v_pk_fma_f32 v[226:227], v[66:67], v[184:185], v[226:227]
	v_lshlrev_b32_e32 v208, 16, v178
	v_and_b32_e32 v209, 0xffff0000, v178
	v_lshlrev_b32_e32 v178, 16, v179
	v_and_b32_e32 v179, 0xffff0000, v179
	v_pk_fma_f32 v[226:227], v[56:57], v[182:183], v[226:227]
	v_lshlrev_b32_e32 v220, 16, v176
	v_and_b32_e32 v221, 0xffff0000, v176
	v_lshlrev_b32_e32 v176, 16, v177
	v_and_b32_e32 v177, 0xffff0000, v177
	v_pk_fma_f32 v[226:227], v[58:59], v[178:179], v[226:227]
	v_lshlrev_b32_e32 v222, 16, v174
	v_and_b32_e32 v223, 0xffff0000, v174
	v_lshlrev_b32_e32 v174, 16, v175
	v_and_b32_e32 v175, 0xffff0000, v175
	v_pk_fma_f32 v[226:227], v[62:63], v[176:177], v[226:227]
	v_lshlrev_b32_e32 v224, 16, v172
	v_and_b32_e32 v225, 0xffff0000, v172
	v_lshlrev_b32_e32 v172, 16, v173
	v_and_b32_e32 v173, 0xffff0000, v173
	v_pk_fma_f32 v[226:227], v[64:65], v[174:175], v[226:227]
	v_lshl_add_u64 v[120:121], v[120:121], 0, s[36:37]
	v_lshlrev_b32_e32 v134, 16, v170
	v_and_b32_e32 v135, 0xffff0000, v170
	v_lshlrev_b32_e32 v170, 16, v171
	v_and_b32_e32 v171, 0xffff0000, v171
	v_pk_fma_f32 v[226:227], v[72:73], v[172:173], v[226:227]
	global_store_dword v[120:121], v229, off sc1 nt
	v_lshlrev_b32_e32 v120, 16, v168
	v_and_b32_e32 v121, 0xffff0000, v168
	v_lshlrev_b32_e32 v168, 16, v169
	v_and_b32_e32 v169, 0xffff0000, v169
	v_pk_fma_f32 v[226:227], v[74:75], v[170:171], v[226:227]
	v_lshlrev_b32_e32 v122, 16, v164
	v_and_b32_e32 v123, 0xffff0000, v164
	v_lshlrev_b32_e32 v164, 16, v165
	v_and_b32_e32 v165, 0xffff0000, v165
	v_pk_fma_f32 v[226:227], v[76:77], v[168:169], v[226:227]
	v_lshlrev_b32_e32 v124, 16, v162
	v_and_b32_e32 v125, 0xffff0000, v162
	v_lshlrev_b32_e32 v162, 16, v163
	v_and_b32_e32 v163, 0xffff0000, v163
	v_pk_fma_f32 v[226:227], v[102:103], v[164:165], v[226:227]
	v_lshlrev_b32_e32 v126, 16, v142
	v_and_b32_e32 v127, 0xffff0000, v142
	v_lshlrev_b32_e32 v142, 16, v143
	v_and_b32_e32 v143, 0xffff0000, v143
	v_pk_fma_f32 v[226:227], v[78:79], v[162:163], v[226:227]
	v_lshlrev_b32_e32 v128, 16, v140
	v_and_b32_e32 v129, 0xffff0000, v140
	v_lshlrev_b32_e32 v140, 16, v141
	v_and_b32_e32 v141, 0xffff0000, v141
	v_pk_fma_f32 v[226:227], v[80:81], v[142:143], v[226:227]
	v_lshlrev_b32_e32 v130, 16, v138
	v_and_b32_e32 v131, 0xffff0000, v138
	v_lshlrev_b32_e32 v138, 16, v139
	v_and_b32_e32 v139, 0xffff0000, v139
	v_pk_fma_f32 v[226:227], v[82:83], v[140:141], v[226:227]
	v_lshlrev_b32_e32 v132, 16, v136
	v_and_b32_e32 v133, 0xffff0000, v136
	v_lshlrev_b32_e32 v136, 16, v137
	v_and_b32_e32 v137, 0xffff0000, v137
	v_pk_fma_f32 v[226:227], v[100:101], v[138:139], v[226:227]
	v_lshlrev_b32_e32 v180, 16, v166
	v_pk_fma_f32 v[226:227], v[84:85], v[136:137], v[226:227]
	v_and_b32_e32 v181, 0xffff0000, v166
	v_pk_fma_f32 v[226:227], v[86:87], v[132:133], v[226:227]
	v_lshlrev_b32_e32 v166, 16, v167
	v_pk_fma_f32 v[226:227], v[92:93], v[130:131], v[226:227]
	v_and_b32_e32 v167, 0xffff0000, v167
	v_pk_fma_f32 v[226:227], v[98:99], v[128:129], v[226:227]
	s_nop 0
	v_pk_fma_f32 v[226:227], v[88:89], v[126:127], v[226:227]
	s_nop 0
	v_pk_fma_f32 v[226:227], v[90:91], v[124:125], v[226:227]
	s_nop 0
	v_pk_fma_f32 v[226:227], v[94:95], v[122:123], v[226:227]
	s_nop 0
	v_pk_fma_f32 v[226:227], v[96:97], v[120:121], v[226:227]
	s_nop 0
	v_pk_fma_f32 v[226:227], v[104:105], v[134:135], v[226:227]
	s_nop 0
	v_pk_fma_f32 v[226:227], v[106:107], v[166:167], v[226:227]
	s_nop 0
	v_pk_fma_f32 v[226:227], v[108:109], v[180:181], v[226:227]
	s_nop 0
	v_pk_fma_f32 v[226:227], v[114:115], v[224:225], v[226:227]
	s_nop 0
	v_pk_fma_f32 v[226:227], v[110:111], v[222:223], v[226:227]
	s_nop 0
	v_pk_fma_f32 v[226:227], v[112:113], v[220:221], v[226:227]
	s_nop 0
	v_pk_fma_f32 v[208:209], v[116:117], v[208:209], v[226:227]
	v_lshlrev_b32_e32 v226, 16, v218
	v_and_b32_e32 v227, 0xffff0000, v218
	v_pk_fma_f32 v[218:219], v[68:69], v[226:227], v[118:119]
	s_nop 0
	v_pk_fma_f32 v[218:219], v[70:71], v[190:191], v[218:219]
	s_nop 0
	v_pk_fma_f32 v[218:219], v[60:61], v[188:189], v[218:219]
	s_nop 0
	v_pk_fma_f32 v[218:219], v[66:67], v[186:187], v[218:219]
	s_nop 0
	v_pk_fma_f32 v[218:219], v[56:57], v[184:185], v[218:219]
	s_nop 0
	v_pk_fma_f32 v[218:219], v[58:59], v[182:183], v[218:219]
	s_nop 0
	v_pk_fma_f32 v[218:219], v[62:63], v[178:179], v[218:219]
	s_nop 0
	v_pk_fma_f32 v[218:219], v[64:65], v[176:177], v[218:219]
	s_nop 0
	v_pk_fma_f32 v[218:219], v[72:73], v[174:175], v[218:219]
	s_nop 0
	v_pk_fma_f32 v[218:219], v[74:75], v[172:173], v[218:219]
	s_nop 0
	v_pk_fma_f32 v[218:219], v[76:77], v[170:171], v[218:219]
	s_nop 0
	v_pk_fma_f32 v[218:219], v[102:103], v[168:169], v[218:219]
	s_nop 0
	v_pk_fma_f32 v[218:219], v[78:79], v[164:165], v[218:219]
	s_nop 0
	v_pk_fma_f32 v[218:219], v[80:81], v[162:163], v[218:219]
	s_nop 0
	v_pk_fma_f32 v[218:219], v[82:83], v[142:143], v[218:219]
	s_nop 0
	v_pk_fma_f32 v[218:219], v[100:101], v[140:141], v[218:219]
	s_nop 0
	v_pk_fma_f32 v[218:219], v[84:85], v[138:139], v[218:219]
	s_nop 0
	v_pk_fma_f32 v[218:219], v[86:87], v[136:137], v[218:219]
; __device__ __forceinline__ f32x2 bf2x2(unsigned w) { return (f32x2){__builtin_bit_cast(float, w << 16), __builtin_bit_cast(float, w & 0xffff0000u)}; }
; __device__ __forceinline__ void pc_pass(int Q, const bf16* UG, bf16* A2, const float* cw, const float* cbias, LAS float* Yw, int mt, int ts, int lane) {
;     ...
;     f32x2 y[8];
; #pragma unroll
;     for (int t = 0; t < 8; ++t) y[t] = cb;
; #pragma unroll
;     for (int i = 0; i < 38; ++i) { const f32x2 gv = bf2x2(graw[i]);
; #pragma unroll
;         for (int t = 0; t < 8; ++t) if (i - t >= 0 && i - t < 31) y[t] = __builtin_elementwise_fma(w[i - t], gv, y[t]); }
	s_nop 0
	v_pk_fma_f32 v[218:219], v[92:93], v[132:133], v[218:219]
	s_nop 0
	v_pk_fma_f32 v[218:219], v[98:99], v[130:131], v[218:219]
	s_nop 0
	v_pk_fma_f32 v[218:219], v[88:89], v[128:129], v[218:219]
	s_nop 0
	v_pk_fma_f32 v[218:219], v[90:91], v[126:127], v[218:219]
	s_nop 0
	v_pk_fma_f32 v[218:219], v[94:95], v[124:125], v[218:219]
	s_nop 0
	v_pk_fma_f32 v[218:219], v[96:97], v[122:123], v[218:219]
	s_nop 0
	v_pk_fma_f32 v[218:219], v[104:105], v[120:121], v[218:219]
	s_nop 0
	v_pk_fma_f32 v[218:219], v[106:107], v[134:135], v[218:219]
	s_nop 0
	v_pk_fma_f32 v[218:219], v[108:109], v[166:167], v[218:219]
	s_nop 0
	v_pk_fma_f32 v[218:219], v[114:115], v[180:181], v[218:219]
	s_nop 0
	v_pk_fma_f32 v[218:219], v[110:111], v[224:225], v[218:219]
	s_nop 0
	v_pk_fma_f32 v[218:219], v[112:113], v[222:223], v[218:219]
	s_nop 0
	v_pk_fma_f32 v[218:219], v[116:117], v[220:221], v[218:219]
	v_lshlrev_b32_e32 v220, 16, v217
	v_and_b32_e32 v221, 0xffff0000, v217
	v_pk_fma_f32 v[228:229], v[68:69], v[220:221], v[118:119]
	s_nop 0
	v_pk_fma_f32 v[228:229], v[70:71], v[226:227], v[228:229]
	s_nop 0
	v_pk_fma_f32 v[228:229], v[60:61], v[190:191], v[228:229]
	s_nop 0
	v_pk_fma_f32 v[228:229], v[66:67], v[188:189], v[228:229]
	s_nop 0
	v_pk_fma_f32 v[228:229], v[56:57], v[186:187], v[228:229]
	s_nop 0
	v_pk_fma_f32 v[228:229], v[58:59], v[184:185], v[228:229]
	s_nop 0
	v_pk_fma_f32 v[228:229], v[62:63], v[182:183], v[228:229]
	s_nop 0
	v_pk_fma_f32 v[228:229], v[64:65], v[178:179], v[228:229]
	s_nop 0
	v_pk_fma_f32 v[228:229], v[72:73], v[176:177], v[228:229]
	s_nop 0
	v_pk_fma_f32 v[228:229], v[74:75], v[174:175], v[228:229]
	s_nop 0
	v_pk_fma_f32 v[228:229], v[76:77], v[172:173], v[228:229]
	s_nop 0
	v_pk_fma_f32 v[228:229], v[102:103], v[170:171], v[228:229]
	s_nop 0
	v_pk_fma_f32 v[228:229], v[78:79], v[168:169], v[228:229]
	s_nop 0
	v_pk_fma_f32 v[228:229], v[80:81], v[164:165], v[228:229]
	s_nop 0
	v_pk_fma_f32 v[228:229], v[82:83], v[162:163], v[228:229]
	s_nop 0
	v_pk_fma_f32 v[228:229], v[100:101], v[142:143], v[228:229]
	s_nop 0
	v_pk_fma_f32 v[228:229], v[84:85], v[140:141], v[228:229]
	s_nop 0
	v_pk_fma_f32 v[228:229], v[86:87], v[138:139], v[228:229]
	s_nop 0
	v_pk_fma_f32 v[228:229], v[92:93], v[136:137], v[228:229]
	s_nop 0
	v_pk_fma_f32 v[228:229], v[98:99], v[132:133], v[228:229]
	s_nop 0
	v_pk_fma_f32 v[228:229], v[88:89], v[130:131], v[228:229]
	s_nop 0
	v_pk_fma_f32 v[228:229], v[90:91], v[128:129], v[228:229]
	s_nop 0
	v_pk_fma_f32 v[228:229], v[94:95], v[126:127], v[228:229]
	s_nop 0
	v_pk_fma_f32 v[228:229], v[96:97], v[124:125], v[228:229]
	s_nop 0
	v_pk_fma_f32 v[228:229], v[104:105], v[122:123], v[228:229]
	s_nop 0
	v_pk_fma_f32 v[228:229], v[106:107], v[120:121], v[228:229]
	s_nop 0
	v_pk_fma_f32 v[228:229], v[108:109], v[134:135], v[228:229]
	s_nop 0
	v_pk_fma_f32 v[228:229], v[114:115], v[166:167], v[228:229]
	s_nop 0
	v_pk_fma_f32 v[228:229], v[110:111], v[180:181], v[228:229]
	s_nop 0
	v_pk_fma_f32 v[228:229], v[112:113], v[224:225], v[228:229]
	s_nop 0
	v_pk_fma_f32 v[222:223], v[116:117], v[222:223], v[228:229]
	v_lshlrev_b32_e32 v228, 16, v216
	v_and_b32_e32 v229, 0xffff0000, v216
	v_pk_fma_f32 v[216:217], v[68:69], v[228:229], v[118:119]
	s_nop 0
	v_pk_fma_f32 v[216:217], v[70:71], v[220:221], v[216:217]
	s_nop 0
	v_pk_fma_f32 v[216:217], v[60:61], v[226:227], v[216:217]
	s_nop 0
	v_pk_fma_f32 v[216:217], v[66:67], v[190:191], v[216:217]
	s_nop 0
	v_pk_fma_f32 v[216:217], v[56:57], v[188:189], v[216:217]
	s_nop 0
	v_pk_fma_f32 v[216:217], v[58:59], v[186:187], v[216:217]
	s_nop 0
	v_pk_fma_f32 v[216:217], v[62:63], v[184:185], v[216:217]
	s_nop 0
	v_pk_fma_f32 v[216:217], v[64:65], v[182:183], v[216:217]
	s_nop 0
	v_pk_fma_f32 v[216:217], v[72:73], v[178:179], v[216:217]
	s_nop 0
	v_pk_fma_f32 v[216:217], v[74:75], v[176:177], v[216:217]
	s_nop 0
	v_pk_fma_f32 v[216:217], v[76:77], v[174:175], v[216:217]
	s_nop 0
	v_pk_fma_f32 v[216:217], v[102:103], v[172:173], v[216:217]
	s_nop 0
	v_pk_fma_f32 v[216:217], v[78:79], v[170:171], v[216:217]
	s_nop 0
	v_pk_fma_f32 v[216:217], v[80:81], v[168:169], v[216:217]
	s_nop 0
	v_pk_fma_f32 v[216:217], v[82:83], v[164:165], v[216:217]
	s_nop 0
	v_pk_fma_f32 v[216:217], v[100:101], v[162:163], v[216:217]
	s_nop 0
	v_pk_fma_f32 v[216:217], v[84:85], v[142:143], v[216:217]
	s_nop 0
	v_pk_fma_f32 v[216:217], v[86:87], v[140:141], v[216:217]
	s_nop 0
	v_pk_fma_f32 v[216:217], v[92:93], v[138:139], v[216:217]
	s_nop 0
	v_pk_fma_f32 v[216:217], v[98:99], v[136:137], v[216:217]
	s_nop 0
	v_pk_fma_f32 v[216:217], v[88:89], v[132:133], v[216:217]
	s_nop 0
	v_pk_fma_f32 v[216:217], v[90:91], v[130:131], v[216:217]
	s_nop 0
	v_pk_fma_f32 v[216:217], v[94:95], v[128:129], v[216:217]
	s_nop 0
	v_pk_fma_f32 v[216:217], v[96:97], v[126:127], v[216:217]
	s_nop 0
	v_pk_fma_f32 v[216:217], v[104:105], v[124:125], v[216:217]
	s_nop 0
	v_pk_fma_f32 v[216:217], v[106:107], v[122:123], v[216:217]
	s_nop 0
	v_pk_fma_f32 v[216:217], v[108:109], v[120:121], v[216:217]
	s_nop 0
	v_pk_fma_f32 v[216:217], v[114:115], v[134:135], v[216:217]
	s_nop 0
	v_pk_fma_f32 v[216:217], v[110:111], v[166:167], v[216:217]
	s_nop 0
	v_pk_fma_f32 v[216:217], v[112:113], v[180:181], v[216:217]
	s_nop 0
	v_pk_fma_f32 v[216:217], v[116:117], v[224:225], v[216:217]
	v_lshlrev_b32_e32 v224, 16, v215
	v_and_b32_e32 v225, 0xffff0000, v215
	v_pk_fma_f32 v[230:231], v[68:69], v[224:225], v[118:119]
	s_nop 0
	v_pk_fma_f32 v[230:231], v[70:71], v[228:229], v[230:231]
	s_nop 0
	v_pk_fma_f32 v[230:231], v[60:61], v[220:221], v[230:231]
	s_nop 0
	v_pk_fma_f32 v[230:231], v[66:67], v[226:227], v[230:231]
	s_nop 0
; __device__ __forceinline__ f32x2 bf2x2(unsigned w) { return (f32x2){__builtin_bit_cast(float, w << 16), __builtin_bit_cast(float, w & 0xffff0000u)}; }
; __device__ __forceinline__ void pc_pass(int Q, const bf16* UG, bf16* A2, const float* cw, const float* cbias, LAS float* Yw, int mt, int ts, int lane) {
;     ...
;     f32x2 y[8];
; #pragma unroll
;     for (int t = 0; t < 8; ++t) y[t] = cb;
; #pragma unroll
;     for (int i = 0; i < 38; ++i) { const f32x2 gv = bf2x2(graw[i]);
; #pragma unroll
;         for (int t = 0; t < 8; ++t) if (i - t >= 0 && i - t < 31) y[t] = __builtin_elementwise_fma(w[i - t], gv, y[t]); }
	v_pk_fma_f32 v[230:231], v[56:57], v[190:191], v[230:231]
	s_nop 0
	v_pk_fma_f32 v[230:231], v[58:59], v[188:189], v[230:231]
	s_nop 0
	v_pk_fma_f32 v[230:231], v[62:63], v[186:187], v[230:231]
	s_nop 0
	v_pk_fma_f32 v[230:231], v[64:65], v[184:185], v[230:231]
	s_nop 0
	v_pk_fma_f32 v[230:231], v[72:73], v[182:183], v[230:231]
	s_nop 0
	v_pk_fma_f32 v[230:231], v[74:75], v[178:179], v[230:231]
	s_nop 0
	v_pk_fma_f32 v[230:231], v[76:77], v[176:177], v[230:231]
	s_nop 0
	v_pk_fma_f32 v[230:231], v[102:103], v[174:175], v[230:231]
	s_nop 0
	v_pk_fma_f32 v[230:231], v[78:79], v[172:173], v[230:231]
	s_nop 0
	v_pk_fma_f32 v[230:231], v[80:81], v[170:171], v[230:231]
	s_nop 0
	v_pk_fma_f32 v[230:231], v[82:83], v[168:169], v[230:231]
	s_nop 0
	v_pk_fma_f32 v[230:231], v[100:101], v[164:165], v[230:231]
	s_nop 0
	v_pk_fma_f32 v[230:231], v[84:85], v[162:163], v[230:231]
	s_nop 0
	v_pk_fma_f32 v[230:231], v[86:87], v[142:143], v[230:231]
	s_nop 0
	v_pk_fma_f32 v[230:231], v[92:93], v[140:141], v[230:231]
	s_nop 0
	v_pk_fma_f32 v[230:231], v[98:99], v[138:139], v[230:231]
	s_nop 0
	v_pk_fma_f32 v[230:231], v[88:89], v[136:137], v[230:231]
	s_nop 0
	v_pk_fma_f32 v[230:231], v[90:91], v[132:133], v[230:231]
	s_nop 0
	v_pk_fma_f32 v[230:231], v[94:95], v[130:131], v[230:231]
	s_nop 0
	v_pk_fma_f32 v[230:231], v[96:97], v[128:129], v[230:231]
	s_nop 0
	v_pk_fma_f32 v[230:231], v[104:105], v[126:127], v[230:231]
	s_nop 0
	v_pk_fma_f32 v[230:231], v[106:107], v[124:125], v[230:231]
	s_nop 0
	v_pk_fma_f32 v[230:231], v[108:109], v[122:123], v[230:231]
	s_nop 0
	v_pk_fma_f32 v[230:231], v[114:115], v[120:121], v[230:231]
	s_nop 0
	v_pk_fma_f32 v[230:231], v[110:111], v[134:135], v[230:231]
	s_nop 0
	v_pk_fma_f32 v[230:231], v[112:113], v[166:167], v[230:231]
	s_nop 0
	v_pk_fma_f32 v[180:181], v[116:117], v[180:181], v[230:231]
	v_lshlrev_b32_e32 v230, 16, v214
	v_and_b32_e32 v231, 0xffff0000, v214
	v_pk_fma_f32 v[214:215], v[68:69], v[230:231], v[118:119]
	s_nop 0
	v_pk_fma_f32 v[214:215], v[70:71], v[224:225], v[214:215]
	s_nop 0
	v_pk_fma_f32 v[214:215], v[60:61], v[228:229], v[214:215]
	s_nop 0
	v_pk_fma_f32 v[214:215], v[66:67], v[220:221], v[214:215]
	s_nop 0
	v_pk_fma_f32 v[214:215], v[56:57], v[226:227], v[214:215]
	s_nop 0
	v_pk_fma_f32 v[214:215], v[58:59], v[190:191], v[214:215]
	s_nop 0
	v_pk_fma_f32 v[214:215], v[62:63], v[188:189], v[214:215]
	s_nop 0
	v_pk_fma_f32 v[214:215], v[64:65], v[186:187], v[214:215]
	s_nop 0
	v_pk_fma_f32 v[214:215], v[72:73], v[184:185], v[214:215]
	s_nop 0
	v_pk_fma_f32 v[214:215], v[74:75], v[182:183], v[214:215]
	s_nop 0
	v_pk_fma_f32 v[214:215], v[76:77], v[178:179], v[214:215]
	s_nop 0
	v_pk_fma_f32 v[214:215], v[102:103], v[176:177], v[214:215]
	s_nop 0
	v_pk_fma_f32 v[214:215], v[78:79], v[174:175], v[214:215]
	s_nop 0
	v_pk_fma_f32 v[214:215], v[80:81], v[172:173], v[214:215]
	s_nop 0
	v_pk_fma_f32 v[214:215], v[82:83], v[170:171], v[214:215]
	s_nop 0
	v_pk_fma_f32 v[214:215], v[100:101], v[168:169], v[214:215]
	s_nop 0
	v_pk_fma_f32 v[214:215], v[84:85], v[164:165], v[214:215]
	s_nop 0
	v_pk_fma_f32 v[214:215], v[86:87], v[162:163], v[214:215]
	s_nop 0
	v_pk_fma_f32 v[214:215], v[92:93], v[142:143], v[214:215]
	s_nop 0
	v_pk_fma_f32 v[214:215], v[98:99], v[140:141], v[214:215]
	s_nop 0
	v_pk_fma_f32 v[214:215], v[88:89], v[138:139], v[214:215]
	s_nop 0
	v_pk_fma_f32 v[214:215], v[90:91], v[136:137], v[214:215]
	s_nop 0
	v_pk_fma_f32 v[214:215], v[94:95], v[132:133], v[214:215]
	s_nop 0
	v_pk_fma_f32 v[214:215], v[96:97], v[130:131], v[214:215]
	s_nop 0
	v_pk_fma_f32 v[214:215], v[104:105], v[128:129], v[214:215]
	s_nop 0
	v_pk_fma_f32 v[214:215], v[106:107], v[126:127], v[214:215]
	s_nop 0
	v_pk_fma_f32 v[214:215], v[108:109], v[124:125], v[214:215]
	s_nop 0
	v_pk_fma_f32 v[214:215], v[114:115], v[122:123], v[214:215]
	s_nop 0
	v_pk_fma_f32 v[214:215], v[110:111], v[120:121], v[214:215]
	s_nop 0
	v_pk_fma_f32 v[214:215], v[112:113], v[134:135], v[214:215]
	s_nop 0
	v_pk_fma_f32 v[166:167], v[116:117], v[166:167], v[214:215]
	v_lshlrev_b32_e32 v214, 16, v213
	v_and_b32_e32 v215, 0xffff0000, v213
	v_pk_fma_f32 v[232:233], v[68:69], v[214:215], v[118:119]
	s_nop 0
	v_pk_fma_f32 v[232:233], v[70:71], v[230:231], v[232:233]
	s_nop 0
	v_pk_fma_f32 v[232:233], v[60:61], v[224:225], v[232:233]
	s_nop 0
	v_pk_fma_f32 v[232:233], v[66:67], v[228:229], v[232:233]
; #define LAS __attribute__((address_space(3)))
; __device__ __forceinline__ f32x2 bf2x2(unsigned w) { return (f32x2){__builtin_bit_cast(float, w << 16), __builtin_bit_cast(float, w & 0xffff0000u)}; }
; #define PC_FENCE() do { asm volatile("" ::: "memory"); __builtin_amdgcn_sched_barrier(0); } while (0)
; __device__ __forceinline__ void pc_pass(int Q, const bf16* UG, bf16* A2, const float* cw, const float* cbias, LAS float* Yw, int mt, int ts, int lane) {
;     ...
;     for (int i = 0; i < 38; ++i) { const f32x2 gv = bf2x2(graw[i]);
; #pragma unroll
;         for (int t = 0; t < 8; ++t) if (i - t >= 0 && i - t < 31) y[t] = __builtin_elementwise_fma(w[i - t], gv, y[t]); }
; #pragma unroll
;     for (int t = 0; t < 8; ++t) *(LAS f32x2*)(Yw + t * 512 + c0) = y[t];
; __device__ __forceinline__ void poolconv_phase(CArgs* a, LAS unsigned char* lds, int G, int tid, int wave, int lane) {
;     ...
;         _Pragma("unroll 1") for (int q = 0; q < 4; ++q) { pc_pass(q, UG, A2, cw, cbias, Yw, mt, ts, lane); PC_FENCE(); }
	s_nop 0
	v_pk_fma_f32 v[232:233], v[56:57], v[220:221], v[232:233]
	s_nop 0
	v_pk_fma_f32 v[232:233], v[58:59], v[226:227], v[232:233]
	s_nop 0
	v_pk_fma_f32 v[232:233], v[62:63], v[190:191], v[232:233]
	s_nop 0
	v_pk_fma_f32 v[232:233], v[64:65], v[188:189], v[232:233]
	s_nop 0
	v_pk_fma_f32 v[232:233], v[72:73], v[186:187], v[232:233]
	s_nop 0
	v_pk_fma_f32 v[232:233], v[74:75], v[184:185], v[232:233]
	s_nop 0
	v_pk_fma_f32 v[232:233], v[76:77], v[182:183], v[232:233]
	s_nop 0
	v_pk_fma_f32 v[232:233], v[102:103], v[178:179], v[232:233]
	s_nop 0
	v_pk_fma_f32 v[232:233], v[78:79], v[176:177], v[232:233]
	s_nop 0
	v_pk_fma_f32 v[232:233], v[80:81], v[174:175], v[232:233]
	s_nop 0
	v_pk_fma_f32 v[232:233], v[82:83], v[172:173], v[232:233]
	s_nop 0
	v_pk_fma_f32 v[232:233], v[100:101], v[170:171], v[232:233]
	s_nop 0
	v_pk_fma_f32 v[232:233], v[84:85], v[168:169], v[232:233]
	s_nop 0
	v_pk_fma_f32 v[232:233], v[86:87], v[164:165], v[232:233]
	s_nop 0
	v_pk_fma_f32 v[232:233], v[92:93], v[162:163], v[232:233]
	s_nop 0
	v_pk_fma_f32 v[232:233], v[98:99], v[142:143], v[232:233]
	s_nop 0
	v_pk_fma_f32 v[232:233], v[88:89], v[140:141], v[232:233]
	s_nop 0
	v_pk_fma_f32 v[232:233], v[90:91], v[138:139], v[232:233]
	s_nop 0
	v_pk_fma_f32 v[232:233], v[94:95], v[136:137], v[232:233]
	s_nop 0
	v_pk_fma_f32 v[232:233], v[96:97], v[132:133], v[232:233]
	s_nop 0
	v_pk_fma_f32 v[232:233], v[104:105], v[130:131], v[232:233]
	s_nop 0
	v_pk_fma_f32 v[232:233], v[106:107], v[128:129], v[232:233]
	s_nop 0
	v_pk_fma_f32 v[232:233], v[108:109], v[126:127], v[232:233]
	s_nop 0
	v_pk_fma_f32 v[232:233], v[114:115], v[124:125], v[232:233]
	s_nop 0
	v_pk_fma_f32 v[232:233], v[110:111], v[122:123], v[232:233]
	s_nop 0
	v_pk_fma_f32 v[232:233], v[112:113], v[120:121], v[232:233]
	s_nop 0
	v_pk_fma_f32 v[134:135], v[116:117], v[134:135], v[232:233]
	v_lshlrev_b32_e32 v232, 16, v212
	v_and_b32_e32 v233, 0xffff0000, v212
	v_pk_fma_f32 v[68:69], v[68:69], v[232:233], v[118:119]
	s_nop 0
	v_pk_fma_f32 v[68:69], v[70:71], v[214:215], v[68:69]
	s_nop 0
	v_pk_fma_f32 v[60:61], v[60:61], v[230:231], v[68:69]
	s_nop 0
	v_pk_fma_f32 v[60:61], v[66:67], v[224:225], v[60:61]
	s_nop 0
	v_pk_fma_f32 v[56:57], v[56:57], v[228:229], v[60:61]
	s_nop 0
	v_pk_fma_f32 v[56:57], v[58:59], v[220:221], v[56:57]
	v_lshl_add_u32 v58, v211, 3, s50
	v_pk_fma_f32 v[56:57], v[62:63], v[226:227], v[56:57]
	s_nop 0
	v_pk_fma_f32 v[56:57], v[64:65], v[190:191], v[56:57]
	s_nop 0
	v_pk_fma_f32 v[56:57], v[72:73], v[188:189], v[56:57]
	s_nop 0
	v_pk_fma_f32 v[56:57], v[74:75], v[186:187], v[56:57]
	s_nop 0
	v_pk_fma_f32 v[56:57], v[76:77], v[184:185], v[56:57]
	s_nop 0
	v_pk_fma_f32 v[56:57], v[102:103], v[182:183], v[56:57]
	s_nop 0
	v_pk_fma_f32 v[56:57], v[78:79], v[178:179], v[56:57]
	s_nop 0
	v_pk_fma_f32 v[56:57], v[80:81], v[176:177], v[56:57]
	s_nop 0
	v_pk_fma_f32 v[56:57], v[82:83], v[174:175], v[56:57]
	s_nop 0
	v_pk_fma_f32 v[56:57], v[100:101], v[172:173], v[56:57]
	s_nop 0
	v_pk_fma_f32 v[56:57], v[84:85], v[170:171], v[56:57]
	s_nop 0
	v_pk_fma_f32 v[56:57], v[86:87], v[168:169], v[56:57]
	s_nop 0
	v_pk_fma_f32 v[56:57], v[92:93], v[164:165], v[56:57]
	s_nop 0
	v_pk_fma_f32 v[56:57], v[98:99], v[162:163], v[56:57]
	s_nop 0
	v_pk_fma_f32 v[56:57], v[88:89], v[142:143], v[56:57]
	s_nop 0
	v_pk_fma_f32 v[56:57], v[90:91], v[140:141], v[56:57]
	s_nop 0
	v_pk_fma_f32 v[56:57], v[94:95], v[138:139], v[56:57]
	s_nop 0
	v_pk_fma_f32 v[56:57], v[96:97], v[136:137], v[56:57]
	s_nop 0
	v_pk_fma_f32 v[56:57], v[104:105], v[132:133], v[56:57]
	s_nop 0
	v_pk_fma_f32 v[56:57], v[106:107], v[130:131], v[56:57]
	s_nop 0
	v_pk_fma_f32 v[56:57], v[108:109], v[128:129], v[56:57]
	s_nop 0
	v_pk_fma_f32 v[56:57], v[114:115], v[126:127], v[56:57]
	s_nop 0
	v_pk_fma_f32 v[56:57], v[110:111], v[124:125], v[56:57]
	s_nop 0
	v_pk_fma_f32 v[56:57], v[112:113], v[122:123], v[56:57]
	s_nop 0
	v_pk_fma_f32 v[56:57], v[116:117], v[120:121], v[56:57]
	ds_write2st64_b64 v58, v[56:57], v[134:135] offset1:4
	ds_write2st64_b64 v58, v[166:167], v[180:181] offset0:8 offset1:12
	ds_write2st64_b64 v58, v[216:217], v[222:223] offset0:16 offset1:20
	ds_write2st64_b64 v58, v[218:219], v[208:209] offset0:24 offset1:28
	s_add_i32 s51, s51, 1
	s_addk_i32 s33, 0x80
	s_addk_i32 s50, 0x200
	s_cmp_eq_u32 s51, 4
	s_cbranch_scc1 .LBB0_243

; #define PC_POOL(WIN) do { _Pragma("unroll") for (int t = 0; t < 8; ++t) { const f32x2 ut = bf2x2(uraw[15 + t]); f32x2 s = ut; _Pragma("unroll") for (int j = 1; j < WIN; ++j) s += bf2x2(uraw[15 + t - j]); \
;         const int cnt = min(ts + t + 1, WIN); const f32x2 p = s * __builtin_amdgcn_rcpf((float)cnt) - ut; *(unsigned*)(A2 + (size_t)(mt + t) * 1024 + c0) = pk2(p.x, p.y); } } while (0)
; __device__ __forceinline__ void pc_pass(int Q, const bf16* UG, bf16* A2, const float* cw, const float* cbias, LAS float* Yw, int mt, int ts, int lane) {
;     ...
;     f32x2 w[31]; unsigned graw[38], uraw[23];
; #pragma unroll
;     for (int i = 0; i < 38; ++i) { const int t = ts - 30 + i; graw[i] = (t >= 0) ? __builtin_nontemporal_load((const unsigned*)(UG + (size_t)(mt - 30 + i) * 1024 + 512 + c0)) : 0u; }
; #pragma unroll
;     for (int i = 0; i < 23; ++i) { const int t = ts - 15 + i; uraw[i] = (t >= 0) ? __builtin_nontemporal_load((const unsigned*)(UG + (size_t)(mt - 15 + i) * 1024 + c0)) : 0u; }
; #pragma unroll
;     for (int j = 0; j < 31; ++j) w[j] = *(const f32x2*)(cw + j * 512 + c0);
;     const f32x2 cb = *(const f32x2*)(cbias + c0);
;     ...
;     if (Q == 0) PC_POOL(2); else if (Q == 1) PC_POOL(4); else if (Q == 2) PC_POOL(8); else PC_POOL(16);
.LBB0_217:
	v_readlane_b32 s12, v253, 23
	v_lshlrev_b64 v[118:119], 2, v[120:121]
	v_readlane_b32 s13, v253, 24
	v_lshl_add_u64 v[58:59], v[56:57], 0, s[34:35]
	v_lshl_add_u64 v[64:65], v[56:57], 0, s[78:79]
	v_lshl_add_u64 v[114:115], s[12:13], 0, v[118:119]
	s_movk_i32 s12, 0x1000
	v_lshl_add_u64 v[60:61], v[56:57], 0, s[76:77]
	v_lshl_add_u64 v[62:63], v[56:57], 0, s[66:67]
	v_lshl_add_u64 v[66:67], v[56:57], 0, s[70:71]
	v_lshl_add_u64 v[68:69], v[56:57], 0, s[64:65]
	v_lshl_add_u64 v[70:71], v[56:57], 0, s[30:31]
	v_lshl_add_u64 v[56:57], v[56:57], 0, s[36:37]
	global_load_dword v125, v[58:59], off nt
	global_load_dword v190, v[60:61], off nt
	global_load_dword v188, v[62:63], off nt
	global_load_dword v186, v[64:65], off nt
	global_load_dword v184, v[66:67], off nt
	global_load_dword v182, v[68:69], off nt
	global_load_dword v181, v[70:71], off nt
	global_load_dword v180, v[56:57], off nt
	v_add_co_u32_e32 v64, vcc, s12, v114
	s_movk_i32 s12, 0x2000
	s_nop 0
	v_addc_co_u32_e32 v65, vcc, 0, v115, vcc
	v_add_co_u32_e32 v58, vcc, s12, v114
	s_movk_i32 s12, 0x3000
	s_nop 0
	v_addc_co_u32_e32 v59, vcc, 0, v115, vcc
	v_add_co_u32_e32 v72, vcc, s12, v114
	s_movk_i32 s12, 0x4000
	s_nop 0
	v_addc_co_u32_e32 v73, vcc, 0, v115, vcc
	v_add_co_u32_e32 v74, vcc, s12, v114
	s_movk_i32 s12, 0x5000
	s_nop 0
	v_addc_co_u32_e32 v75, vcc, 0, v115, vcc
	v_add_co_u32_e32 v96, vcc, s12, v114
	s_movk_i32 s12, 0x6000
	s_nop 0
	v_addc_co_u32_e32 v97, vcc, 0, v115, vcc
	v_add_co_u32_e32 v80, vcc, s12, v114
	s_movk_i32 s12, 0x7000
	s_nop 0
	v_addc_co_u32_e32 v81, vcc, 0, v115, vcc
	v_add_co_u32_e32 v98, vcc, s12, v114
	s_mov_b32 s12, 0x8000
	s_nop 0
	v_addc_co_u32_e32 v99, vcc, 0, v115, vcc
	v_add_co_u32_e32 v86, vcc, s12, v114
	s_mov_b32 s12, 0x9000
	s_nop 0
	v_addc_co_u32_e32 v87, vcc, 0, v115, vcc
	v_add_co_u32_e32 v104, vcc, s12, v114
	s_mov_b32 s12, 0xa000
	s_nop 0
	v_addc_co_u32_e32 v105, vcc, 0, v115, vcc
	v_add_co_u32_e32 v90, vcc, s12, v114
	s_mov_b32 s12, 0xb000
	s_nop 0
	v_addc_co_u32_e32 v91, vcc, 0, v115, vcc
	v_add_co_u32_e32 v106, vcc, s12, v114
	s_mov_b32 s12, 0xc000
	s_nop 0
	v_addc_co_u32_e32 v107, vcc, 0, v115, vcc
	v_add_co_u32_e32 v108, vcc, s12, v114
	s_mov_b32 s12, 0xd000
	s_nop 0
	v_addc_co_u32_e32 v109, vcc, 0, v115, vcc
	v_add_co_u32_e32 v116, vcc, s12, v114
	global_load_dwordx2 v[60:61], v[58:59], off offset:-4096
	global_load_dwordx2 v[56:57], v[58:59], off
	s_nop 0
	global_load_dwordx2 v[58:59], v[58:59], off offset:2048
	s_nop 0
	global_load_dwordx2 v[62:63], v[74:75], off offset:-4096
	global_load_dwordx2 v[68:69], v[114:115], off
	global_load_dwordx2 v[70:71], v[114:115], off offset:2048
	global_load_dwordx2 v[66:67], v[64:65], off offset:2048
	s_nop 0
	global_load_dwordx2 v[64:65], v[72:73], off offset:2048
	s_nop 0
	global_load_dwordx2 v[72:73], v[74:75], off
	s_nop 0
	global_load_dwordx2 v[74:75], v[74:75], off offset:2048
	s_nop 0
	global_load_dwordx2 v[76:77], v[80:81], off offset:-4096
	global_load_dwordx2 v[78:79], v[80:81], off
	s_nop 0
	global_load_dwordx2 v[80:81], v[80:81], off offset:2048
	s_nop 0
	global_load_dwordx2 v[82:83], v[86:87], off offset:-4096
	global_load_dwordx2 v[84:85], v[86:87], off
	s_nop 0
	global_load_dwordx2 v[86:87], v[86:87], off offset:2048
	s_nop 0
	global_load_dwordx2 v[92:93], v[90:91], off offset:-4096
	global_load_dwordx2 v[88:89], v[90:91], off
	s_nop 0
	global_load_dwordx2 v[90:91], v[90:91], off offset:2048
	s_nop 0
	global_load_dwordx2 v[94:95], v[108:109], off offset:-4096
	global_load_dwordx2 v[102:103], v[96:97], off offset:2048
	global_load_dwordx2 v[100:101], v[98:99], off offset:2048
	s_nop 0
	global_load_dwordx2 v[98:99], v[104:105], off offset:2048
	global_load_dwordx2 v[96:97], v[106:107], off offset:2048
	v_addc_co_u32_e32 v117, vcc, 0, v115, vcc
	s_mov_b32 s12, 0xe000
	v_add_co_u32_e32 v112, vcc, s12, v114
	v_readlane_b32 s14, v253, 25
	s_nop 0
	v_addc_co_u32_e32 v113, vcc, 0, v115, vcc
	global_load_dwordx2 v[104:105], v[108:109], off
	global_load_dwordx2 v[106:107], v[108:109], off offset:2048
	s_nop 0
	global_load_dwordx2 v[108:109], v[112:113], off offset:-4096
	global_load_dwordx2 v[110:111], v[112:113], off
	s_nop 0
	global_load_dwordx2 v[112:113], v[112:113], off offset:2048
	v_readlane_b32 s15, v253, 26
	s_mov_b32 s12, 0xf000
	v_add_co_u32_e32 v122, vcc, s12, v114
	v_lshl_add_u64 v[118:119], s[14:15], 0, v[118:119]
	s_nop 0
	v_addc_co_u32_e32 v123, vcc, 0, v115, vcc
	global_load_dwordx2 v[114:115], v[116:117], off offset:2048
	s_nop 0
	global_load_dwordx2 v[116:117], v[122:123], off
	v_readlane_b32 s12, v253, 31
	global_load_dwordx2 v[118:119], v[118:119], off
	v_readlane_b32 s13, v253, 32
	s_waitcnt vmcnt(39)
	v_lshlrev_b32_e32 v122, 16, v125
	v_and_b32_e32 v123, 0xffff0000, v125
	v_lshlrev_b32_e32 v126, 16, v124
	v_and_b32_e32 v127, 0xffff0000, v124
	v_lshl_add_u64 v[120:121], v[120:121], 1, s[12:13]
	v_pk_add_f32 v[124:125], v[126:127], v[122:123]
	s_cmp_lt_i32 s51, 1
	s_mov_b64 s[12:13], -1
	v_readlane_b32 s16, v253, 27
	v_readlane_b32 s17, v253, 28
	v_readlane_b32 s18, v253, 29
	v_readlane_b32 s19, v253, 30
	s_cbranch_scc1 .LBB0_227
	s_cmp_lt_i32 s51, 2
	s_cbranch_scc1 .LBB0_224
	s_cmp_lg_u32 s51, 2
	v_lshlrev_b32_e32 v128, 16, v129
	v_and_b32_e32 v129, 0xffff0000, v129
	v_lshlrev_b32_e32 v130, 16, v131
	v_and_b32_e32 v131, 0xffff0000, v131
	v_lshlrev_b32_e32 v132, 16, v133
	v_and_b32_e32 v133, 0xffff0000, v133
	v_lshlrev_b32_e32 v134, 16, v135
	v_and_b32_e32 v135, 0xffff0000, v135
	s_cbranch_scc0 .LBB0_221
; #define PC_POOL(WIN) do { _Pragma("unroll") for (int t = 0; t < 8; ++t) { const f32x2 ut = bf2x2(uraw[15 + t]); f32x2 s = ut; _Pragma("unroll") for (int j = 1; j < WIN; ++j) s += bf2x2(uraw[15 + t - j]); \
;         const int cnt = min(ts + t + 1, WIN); const f32x2 p = s * __builtin_amdgcn_rcpf((float)cnt) - ut; *(unsigned*)(A2 + (size_t)(mt + t) * 1024 + c0) = pk2(p.x, p.y); } } while (0)
; __device__ __forceinline__ void pc_pass(int Q, const bf16* UG, bf16* A2, const float* cw, const float* cbias, LAS float* Yw, int mt, int ts, int lane) {
;     ...
;     if (Q == 0) PC_POOL(2); else if (Q == 1) PC_POOL(4); else if (Q == 2) PC_POOL(8); else PC_POOL(16);
	v_lshlrev_b32_e32 v208, 16, v220
	v_and_b32_e32 v209, 0xffff0000, v220
	v_pk_add_f32 v[230:231], v[124:125], v[208:209]
	v_lshlrev_b32_e32 v232, 16, v219
	v_and_b32_e32 v233, 0xffff0000, v219
	v_pk_add_f32 v[230:231], v[230:231], v[232:233]
	v_lshlrev_b32_e32 v234, 16, v228
	v_pk_add_f32 v[230:231], v[230:231], v[128:129]
	v_and_b32_e32 v235, 0xffff0000, v228
	v_pk_add_f32 v[230:231], v[230:231], v[130:131]
	v_lshlrev_b32_e32 v236, 16, v226
	v_pk_add_f32 v[230:231], v[230:231], v[132:133]
	v_and_b32_e32 v237, 0xffff0000, v226
	v_pk_add_f32 v[230:231], v[230:231], v[134:135]
	v_lshlrev_b32_e32 v238, 16, v224
	v_pk_add_f32 v[228:229], v[230:231], v[234:235]
	v_lshlrev_b32_e32 v230, 16, v227
	v_and_b32_e32 v231, 0xffff0000, v227
	v_pk_add_f32 v[228:229], v[228:229], v[230:231]
	v_and_b32_e32 v239, 0xffff0000, v224
	v_pk_add_f32 v[226:227], v[228:229], v[236:237]
	v_lshlrev_b32_e32 v228, 16, v225
	v_and_b32_e32 v229, 0xffff0000, v225
	v_pk_add_f32 v[226:227], v[226:227], v[228:229]
	v_lshlrev_b32_e32 v240, 16, v222
	v_pk_add_f32 v[224:225], v[226:227], v[238:239]
	v_lshlrev_b32_e32 v226, 16, v223
	v_and_b32_e32 v227, 0xffff0000, v223
	v_pk_add_f32 v[224:225], v[224:225], v[226:227]
	v_and_b32_e32 v241, 0xffff0000, v222
	v_pk_add_f32 v[222:223], v[224:225], v[240:241]
	v_lshlrev_b32_e32 v224, 16, v221
	v_and_b32_e32 v225, 0xffff0000, v221
	v_pk_add_f32 v[222:223], v[222:223], v[224:225]
	s_mov_b64 s[12:13], 0
	v_pk_fma_f32 v[222:223], v[40:41], v[222:223], v[122:123] neg_lo:[0,0,1] neg_hi:[0,0,1]
	s_nop 0
	v_cvt_pk_bf16_f32 v221, v222, v223
	v_lshl_add_u64 v[222:223], v[120:121], 0, s[34:35]
	global_store_dword v[222:223], v221, off sc1 nt
	s_waitcnt vmcnt(39)
	v_lshlrev_b32_e32 v222, 16, v190
	v_and_b32_e32 v223, 0xffff0000, v190
	v_pk_add_f32 v[224:225], v[122:123], v[222:223]
	s_nop 0
	v_pk_add_f32 v[224:225], v[224:225], v[126:127]
	s_nop 0
	v_pk_add_f32 v[224:225], v[224:225], v[208:209]
	s_nop 0
	v_pk_add_f32 v[224:225], v[224:225], v[232:233]
	s_nop 0
	v_pk_add_f32 v[224:225], v[224:225], v[128:129]
	s_nop 0
	v_pk_add_f32 v[224:225], v[224:225], v[130:131]
	s_nop 0
	v_pk_add_f32 v[224:225], v[224:225], v[132:133]
	s_nop 0
	v_pk_add_f32 v[224:225], v[224:225], v[134:135]
	s_nop 0
	v_pk_add_f32 v[224:225], v[224:225], v[234:235]
	s_nop 0
	v_pk_add_f32 v[224:225], v[224:225], v[230:231]
	s_nop 0
	v_pk_add_f32 v[224:225], v[224:225], v[236:237]
	s_nop 0
	v_pk_add_f32 v[224:225], v[224:225], v[228:229]
	s_nop 0
	v_pk_add_f32 v[224:225], v[224:225], v[238:239]
	s_nop 0
	v_pk_add_f32 v[224:225], v[224:225], v[226:227]
	s_nop 0
	v_pk_add_f32 v[224:225], v[224:225], v[240:241]
	s_nop 0
	v_pk_fma_f32 v[224:225], v[42:43], v[224:225], v[222:223] neg_lo:[0,0,1] neg_hi:[0,0,1]
	s_nop 0
	v_cvt_pk_bf16_f32 v221, v224, v225
	v_lshl_add_u64 v[224:225], v[120:121], 0, s[76:77]
	global_store_dword v[224:225], v221, off sc1 nt
	s_waitcnt vmcnt(39)
	v_lshlrev_b32_e32 v224, 16, v188
	v_and_b32_e32 v225, 0xffff0000, v188
	v_pk_add_f32 v[240:241], v[222:223], v[224:225]
	s_nop 0
	v_pk_add_f32 v[240:241], v[240:241], v[122:123]
	s_nop 0
	v_pk_add_f32 v[240:241], v[240:241], v[126:127]
	s_nop 0
	v_pk_add_f32 v[240:241], v[240:241], v[208:209]
	s_nop 0
	v_pk_add_f32 v[240:241], v[240:241], v[232:233]
	s_nop 0
	v_pk_add_f32 v[240:241], v[240:241], v[128:129]
	s_nop 0
	v_pk_add_f32 v[240:241], v[240:241], v[130:131]
	s_nop 0
	v_pk_add_f32 v[240:241], v[240:241], v[132:133]
	s_nop 0
	v_pk_add_f32 v[240:241], v[240:241], v[134:135]
	s_nop 0
	v_pk_add_f32 v[240:241], v[240:241], v[234:235]
	s_nop 0
	v_pk_add_f32 v[240:241], v[240:241], v[230:231]
	s_nop 0
	v_pk_add_f32 v[240:241], v[240:241], v[236:237]
	s_nop 0
	v_pk_add_f32 v[240:241], v[240:241], v[228:229]
	s_nop 0
	v_pk_add_f32 v[240:241], v[240:241], v[238:239]
	s_nop 0
	v_pk_add_f32 v[226:227], v[240:241], v[226:227]
	s_nop 0
	v_pk_fma_f32 v[226:227], v[44:45], v[226:227], v[224:225] neg_lo:[0,0,1] neg_hi:[0,0,1]
	s_nop 0
	v_cvt_pk_bf16_f32 v221, v226, v227
	v_lshl_add_u64 v[226:227], v[120:121], 0, s[66:67]
	global_store_dword v[226:227], v221, off sc1 nt
	s_waitcnt vmcnt(39)
	v_lshlrev_b32_e32 v226, 16, v186
	v_and_b32_e32 v227, 0xffff0000, v186
	v_pk_add_f32 v[240:241], v[224:225], v[226:227]
	s_nop 0
	v_pk_add_f32 v[240:241], v[240:241], v[222:223]
	s_nop 0
	v_pk_add_f32 v[240:241], v[240:241], v[122:123]
	s_nop 0
	v_pk_add_f32 v[240:241], v[240:241], v[126:127]
	s_nop 0
	v_pk_add_f32 v[240:241], v[240:241], v[208:209]
	s_nop 0
	v_pk_add_f32 v[240:241], v[240:241], v[232:233]
	s_nop 0
	v_pk_add_f32 v[240:241], v[240:241], v[128:129]
	s_nop 0
	v_pk_add_f32 v[240:241], v[240:241], v[130:131]
	s_nop 0
	v_pk_add_f32 v[240:241], v[240:241], v[132:133]
	s_nop 0
	v_pk_add_f32 v[240:241], v[240:241], v[134:135]
	s_nop 0
	v_pk_add_f32 v[240:241], v[240:241], v[234:235]
	s_nop 0
	v_pk_add_f32 v[240:241], v[240:241], v[230:231]
	s_nop 0
	v_pk_add_f32 v[240:241], v[240:241], v[236:237]
	s_nop 0
	v_pk_add_f32 v[240:241], v[240:241], v[228:229]
	s_nop 0
	v_pk_add_f32 v[238:239], v[240:241], v[238:239]
	s_nop 0
	v_pk_fma_f32 v[238:239], v[46:47], v[238:239], v[226:227] neg_lo:[0,0,1] neg_hi:[0,0,1]
	s_nop 0
	v_cvt_pk_bf16_f32 v221, v238, v239
	v_lshl_add_u64 v[238:239], v[120:121], 0, s[78:79]
	global_store_dword v[238:239], v221, off sc1 nt
	s_waitcnt vmcnt(39)
; #define PC_POOL(WIN) do { _Pragma("unroll") for (int t = 0; t < 8; ++t) { const f32x2 ut = bf2x2(uraw[15 + t]); f32x2 s = ut; _Pragma("unroll") for (int j = 1; j < WIN; ++j) s += bf2x2(uraw[15 + t - j]); \
;         const int cnt = min(ts + t + 1, WIN); const f32x2 p = s * __builtin_amdgcn_rcpf((float)cnt) - ut; *(unsigned*)(A2 + (size_t)(mt + t) * 1024 + c0) = pk2(p.x, p.y); } } while (0)
; __device__ __forceinline__ void pc_pass(int Q, const bf16* UG, bf16* A2, const float* cw, const float* cbias, LAS float* Yw, int mt, int ts, int lane) {
;     ...
;     if (Q == 0) PC_POOL(2); else if (Q == 1) PC_POOL(4); else if (Q == 2) PC_POOL(8); else PC_POOL(16);
	v_lshlrev_b32_e32 v238, 16, v184
	v_and_b32_e32 v239, 0xffff0000, v184
	v_pk_add_f32 v[240:241], v[226:227], v[238:239]
	s_nop 0
	v_pk_add_f32 v[240:241], v[240:241], v[224:225]
	s_nop 0
	v_pk_add_f32 v[240:241], v[240:241], v[222:223]
	s_nop 0
	v_pk_add_f32 v[240:241], v[240:241], v[122:123]
	s_nop 0
	v_pk_add_f32 v[240:241], v[240:241], v[126:127]
	s_nop 0
	v_pk_add_f32 v[240:241], v[240:241], v[208:209]
	s_nop 0
	v_pk_add_f32 v[240:241], v[240:241], v[232:233]
	s_nop 0
	v_pk_add_f32 v[240:241], v[240:241], v[128:129]
	s_nop 0
	v_pk_add_f32 v[240:241], v[240:241], v[130:131]
	s_nop 0
	v_pk_add_f32 v[240:241], v[240:241], v[132:133]
	s_nop 0
	v_pk_add_f32 v[240:241], v[240:241], v[134:135]
	s_nop 0
	v_pk_add_f32 v[240:241], v[240:241], v[234:235]
	s_nop 0
	v_pk_add_f32 v[240:241], v[240:241], v[230:231]
	s_nop 0
	v_pk_add_f32 v[240:241], v[240:241], v[236:237]
	s_nop 0
	v_pk_add_f32 v[228:229], v[240:241], v[228:229]
	s_nop 0
	v_pk_fma_f32 v[228:229], v[48:49], v[228:229], v[238:239] neg_lo:[0,0,1] neg_hi:[0,0,1]
	s_nop 0
	v_cvt_pk_bf16_f32 v221, v228, v229
	v_lshl_add_u64 v[228:229], v[120:121], 0, s[70:71]
	global_store_dword v[228:229], v221, off sc1 nt
	s_waitcnt vmcnt(39)
	v_lshlrev_b32_e32 v228, 16, v182
	v_and_b32_e32 v229, 0xffff0000, v182
	v_pk_add_f32 v[240:241], v[238:239], v[228:229]
	s_nop 0
	v_pk_add_f32 v[240:241], v[240:241], v[226:227]
	s_nop 0
	v_pk_add_f32 v[240:241], v[240:241], v[224:225]
	s_nop 0
	v_pk_add_f32 v[240:241], v[240:241], v[222:223]
	s_nop 0
	v_pk_add_f32 v[240:241], v[240:241], v[122:123]
	s_nop 0
	v_pk_add_f32 v[240:241], v[240:241], v[126:127]
	s_nop 0
	v_pk_add_f32 v[240:241], v[240:241], v[208:209]
	s_nop 0
	v_pk_add_f32 v[240:241], v[240:241], v[232:233]
	s_nop 0
	v_pk_add_f32 v[240:241], v[240:241], v[128:129]
	s_nop 0
	v_pk_add_f32 v[240:241], v[240:241], v[130:131]
	s_nop 0
	v_pk_add_f32 v[240:241], v[240:241], v[132:133]
	s_nop 0
	v_pk_add_f32 v[240:241], v[240:241], v[134:135]
	s_nop 0
	v_pk_add_f32 v[240:241], v[240:241], v[234:235]
	s_nop 0
	v_pk_add_f32 v[240:241], v[240:241], v[230:231]
	s_nop 0
	v_pk_add_f32 v[236:237], v[240:241], v[236:237]
	s_nop 0
	v_pk_fma_f32 v[236:237], v[50:51], v[236:237], v[228:229] neg_lo:[0,0,1] neg_hi:[0,0,1]
	s_nop 0
	v_cvt_pk_bf16_f32 v221, v236, v237
	v_lshl_add_u64 v[236:237], v[120:121], 0, s[64:65]
	global_store_dword v[236:237], v221, off sc1 nt
	s_waitcnt vmcnt(39)
	v_lshlrev_b32_e32 v236, 16, v181
	v_and_b32_e32 v237, 0xffff0000, v181
	v_pk_add_f32 v[240:241], v[228:229], v[236:237]
	s_nop 0
	v_pk_add_f32 v[240:241], v[240:241], v[238:239]
	s_nop 0
	v_pk_add_f32 v[240:241], v[240:241], v[226:227]
	s_nop 0
	v_pk_add_f32 v[240:241], v[240:241], v[224:225]
	s_nop 0
	v_pk_add_f32 v[240:241], v[240:241], v[222:223]
	s_nop 0
	v_pk_add_f32 v[240:241], v[240:241], v[122:123]
	s_nop 0
	v_pk_add_f32 v[240:241], v[240:241], v[126:127]
	s_nop 0
	v_pk_add_f32 v[240:241], v[240:241], v[208:209]
	s_nop 0
	v_pk_add_f32 v[240:241], v[240:241], v[232:233]
	s_nop 0
	v_pk_add_f32 v[240:241], v[240:241], v[128:129]
	s_nop 0
	v_pk_add_f32 v[240:241], v[240:241], v[130:131]
	s_nop 0
	v_pk_add_f32 v[240:241], v[240:241], v[132:133]
	s_nop 0
	v_pk_add_f32 v[240:241], v[240:241], v[134:135]
	s_nop 0
	v_pk_add_f32 v[240:241], v[240:241], v[234:235]
	s_nop 0
	v_pk_add_f32 v[230:231], v[240:241], v[230:231]
	s_nop 0
	v_pk_fma_f32 v[230:231], v[52:53], v[230:231], v[236:237] neg_lo:[0,0,1] neg_hi:[0,0,1]
	s_nop 0
	v_cvt_pk_bf16_f32 v221, v230, v231
	v_lshl_add_u64 v[230:231], v[120:121], 0, s[30:31]
	global_store_dword v[230:231], v221, off sc1 nt
	s_waitcnt vmcnt(39)
	v_lshlrev_b32_e32 v230, 16, v180
	v_and_b32_e32 v231, 0xffff0000, v180
	v_pk_add_f32 v[236:237], v[236:237], v[230:231]
	s_nop 0
	v_pk_add_f32 v[228:229], v[236:237], v[228:229]
	s_nop 0
	v_pk_add_f32 v[228:229], v[228:229], v[238:239]
	s_nop 0
	v_pk_add_f32 v[226:227], v[228:229], v[226:227]
	s_nop 0
	v_pk_add_f32 v[224:225], v[226:227], v[224:225]
	s_nop 0
	v_pk_add_f32 v[222:223], v[224:225], v[222:223]
	s_nop 0
	v_pk_add_f32 v[222:223], v[222:223], v[122:123]
	s_nop 0
	v_pk_add_f32 v[222:223], v[222:223], v[126:127]
	s_nop 0
	v_pk_add_f32 v[208:209], v[222:223], v[208:209]
	s_nop 0
	v_pk_add_f32 v[208:209], v[208:209], v[232:233]
	s_nop 0
	v_pk_add_f32 v[208:209], v[208:209], v[128:129]
	s_nop 0
	v_pk_add_f32 v[208:209], v[208:209], v[130:131]
	s_nop 0
	v_pk_add_f32 v[208:209], v[208:209], v[132:133]
	s_nop 0
	v_pk_add_f32 v[208:209], v[208:209], v[134:135]
	s_nop 0
	v_pk_add_f32 v[208:209], v[208:209], v[234:235]
	s_nop 0
	v_pk_fma_f32 v[208:209], v[54:55], v[208:209], v[230:231] neg_lo:[0,0,1] neg_hi:[0,0,1]
	s_nop 0
	v_cvt_pk_bf16_f32 v229, v208, v209
; #define PC_POOL(WIN) do { _Pragma("unroll") for (int t = 0; t < 8; ++t) { const f32x2 ut = bf2x2(uraw[15 + t]); f32x2 s = ut; _Pragma("unroll") for (int j = 1; j < WIN; ++j) s += bf2x2(uraw[15 + t - j]); \
;         const int cnt = min(ts + t + 1, WIN); const f32x2 p = s * __builtin_amdgcn_rcpf((float)cnt) - ut; *(unsigned*)(A2 + (size_t)(mt + t) * 1024 + c0) = pk2(p.x, p.y); } } while (0)
; __device__ __forceinline__ void pc_pass(int Q, const bf16* UG, bf16* A2, const float* cw, const float* cbias, LAS float* Yw, int mt, int ts, int lane) {
;     ...
;     if (Q == 0) PC_POOL(2); else if (Q == 1) PC_POOL(4); else if (Q == 2) PC_POOL(8); else PC_POOL(16);
.LBB0_221:
	s_andn2_b64 vcc, exec, s[12:13]
	s_cbranch_vccnz .LBB0_223
	v_lshlrev_b32_e32 v208, 16, v220
	v_and_b32_e32 v209, 0xffff0000, v220
	v_pk_add_f32 v[222:223], v[124:125], v[208:209]
	v_lshlrev_b32_e32 v224, 16, v219
	v_and_b32_e32 v225, 0xffff0000, v219
	v_pk_add_f32 v[222:223], v[222:223], v[224:225]
	s_mov_b32 s12, 0x3e000000
	v_pk_add_f32 v[222:223], v[222:223], v[128:129]
	s_nop 0
	v_pk_add_f32 v[222:223], v[222:223], v[130:131]
	s_nop 0
	v_pk_add_f32 v[222:223], v[222:223], v[132:133]
	s_nop 0
	v_pk_add_f32 v[134:135], v[222:223], v[134:135]
	s_nop 0
	v_pk_fma_f32 v[134:135], v[16:17], v[134:135], v[122:123] neg_lo:[0,0,1] neg_hi:[0,0,1]
	s_nop 0
	v_cvt_pk_bf16_f32 v221, v134, v135
	v_lshl_add_u64 v[134:135], v[120:121], 0, s[34:35]
	global_store_dword v[134:135], v221, off sc1 nt
	s_waitcnt vmcnt(39)
	v_lshlrev_b32_e32 v134, 16, v190
	v_and_b32_e32 v135, 0xffff0000, v190
	v_pk_add_f32 v[222:223], v[122:123], v[134:135]
	s_nop 0
	v_pk_add_f32 v[222:223], v[222:223], v[126:127]
	s_nop 0
	v_pk_add_f32 v[222:223], v[222:223], v[208:209]
	s_nop 0
	v_pk_add_f32 v[222:223], v[222:223], v[224:225]
	s_nop 0
	v_pk_add_f32 v[222:223], v[222:223], v[128:129]
	s_nop 0
	v_pk_add_f32 v[222:223], v[222:223], v[130:131]
	s_nop 0
	v_pk_add_f32 v[132:133], v[222:223], v[132:133]
	s_nop 0
	v_pk_fma_f32 v[132:133], v[18:19], v[132:133], v[134:135] neg_lo:[0,0,1] neg_hi:[0,0,1]
	s_nop 0
	v_cvt_pk_bf16_f32 v221, v132, v133
	v_lshl_add_u64 v[132:133], v[120:121], 0, s[76:77]
	global_store_dword v[132:133], v221, off sc1 nt
	s_waitcnt vmcnt(39)
	v_lshlrev_b32_e32 v132, 16, v188
	v_and_b32_e32 v133, 0xffff0000, v188
	v_pk_add_f32 v[222:223], v[134:135], v[132:133]
	s_nop 0
	v_pk_add_f32 v[222:223], v[222:223], v[122:123]
	s_nop 0
	v_pk_add_f32 v[222:223], v[222:223], v[126:127]
	s_nop 0
	v_pk_add_f32 v[222:223], v[222:223], v[208:209]
	s_nop 0
	v_pk_add_f32 v[222:223], v[222:223], v[224:225]
	s_nop 0
	v_pk_add_f32 v[222:223], v[222:223], v[128:129]
	s_nop 0
	v_pk_add_f32 v[130:131], v[222:223], v[130:131]
	s_nop 0
	v_pk_fma_f32 v[130:131], v[22:23], v[130:131], v[132:133] neg_lo:[0,0,1] neg_hi:[0,0,1]
	s_nop 0
	v_cvt_pk_bf16_f32 v221, v130, v131
	v_lshl_add_u64 v[130:131], v[120:121], 0, s[66:67]
	global_store_dword v[130:131], v221, off sc1 nt
	s_waitcnt vmcnt(39)
	v_lshlrev_b32_e32 v130, 16, v186
	v_and_b32_e32 v131, 0xffff0000, v186
	v_pk_add_f32 v[222:223], v[132:133], v[130:131]
	s_nop 0
	v_pk_add_f32 v[222:223], v[222:223], v[134:135]
	s_nop 0
	v_pk_add_f32 v[222:223], v[222:223], v[122:123]
	s_nop 0
	v_pk_add_f32 v[222:223], v[222:223], v[126:127]
	s_nop 0
	v_pk_add_f32 v[222:223], v[222:223], v[208:209]
	s_nop 0
	v_pk_add_f32 v[222:223], v[222:223], v[224:225]
	s_nop 0
	v_pk_add_f32 v[128:129], v[222:223], v[128:129]
	s_nop 0
	v_pk_fma_f32 v[128:129], v[24:25], v[128:129], v[130:131] neg_lo:[0,0,1] neg_hi:[0,0,1]
	s_nop 0
	v_cvt_pk_bf16_f32 v221, v128, v129
	v_lshl_add_u64 v[128:129], v[120:121], 0, s[78:79]
	global_store_dword v[128:129], v221, off sc1 nt
	s_waitcnt vmcnt(39)
	v_lshlrev_b32_e32 v128, 16, v184
	v_and_b32_e32 v129, 0xffff0000, v184
	v_pk_add_f32 v[222:223], v[130:131], v[128:129]
	s_nop 0
	v_pk_add_f32 v[222:223], v[222:223], v[132:133]
	s_nop 0
	v_pk_add_f32 v[222:223], v[222:223], v[134:135]
	s_nop 0
	v_pk_add_f32 v[222:223], v[222:223], v[122:123]
	s_nop 0
	v_pk_add_f32 v[222:223], v[222:223], v[126:127]
	s_nop 0
	v_pk_add_f32 v[222:223], v[222:223], v[208:209]
	s_nop 0
	v_pk_add_f32 v[222:223], v[222:223], v[224:225]
	s_nop 0
	v_pk_fma_f32 v[222:223], v[26:27], v[222:223], v[128:129] neg_lo:[0,0,1] neg_hi:[0,0,1]
	s_nop 0
	v_cvt_pk_bf16_f32 v221, v222, v223
	v_lshl_add_u64 v[222:223], v[120:121], 0, s[70:71]
	global_store_dword v[222:223], v221, off sc1 nt
	s_waitcnt vmcnt(39)
	v_lshlrev_b32_e32 v222, 16, v182
	v_and_b32_e32 v223, 0xffff0000, v182
	v_pk_add_f32 v[224:225], v[128:129], v[222:223]
	s_nop 0
	v_pk_add_f32 v[224:225], v[224:225], v[130:131]
	s_nop 0
	v_pk_add_f32 v[224:225], v[224:225], v[132:133]
	s_nop 0
	v_pk_add_f32 v[224:225], v[224:225], v[134:135]
	s_nop 0
	v_pk_add_f32 v[224:225], v[224:225], v[122:123]
	s_nop 0
	v_pk_add_f32 v[224:225], v[224:225], v[126:127]
	s_nop 0
	v_pk_add_f32 v[208:209], v[224:225], v[208:209]
	s_nop 0
	v_pk_fma_f32 v[208:209], v[28:29], v[208:209], v[222:223] neg_lo:[0,0,1] neg_hi:[0,0,1]
	s_nop 0
	v_cvt_pk_bf16_f32 v221, v208, v209
	v_lshl_add_u64 v[208:209], v[120:121], 0, s[64:65]
	global_store_dword v[208:209], v221, off sc1 nt
	s_waitcnt vmcnt(39)
	v_lshlrev_b32_e32 v208, 16, v181
	v_and_b32_e32 v209, 0xffff0000, v181
	v_pk_add_f32 v[224:225], v[222:223], v[208:209]
	s_nop 0
	v_pk_add_f32 v[224:225], v[224:225], v[128:129]
	s_nop 0
	v_pk_add_f32 v[224:225], v[224:225], v[130:131]
	s_nop 0
	v_pk_add_f32 v[224:225], v[224:225], v[132:133]
	s_nop 0
	v_pk_add_f32 v[224:225], v[224:225], v[134:135]
	s_nop 0
	v_pk_add_f32 v[224:225], v[224:225], v[122:123]
	s_nop 0
	v_pk_add_f32 v[224:225], v[224:225], v[126:127]
	s_nop 0
	v_pk_fma_f32 v[224:225], v[30:31], v[224:225], v[208:209] neg_lo:[0,0,1] neg_hi:[0,0,1]
	s_nop 0
	v_cvt_pk_bf16_f32 v221, v224, v225
	v_lshl_add_u64 v[224:225], v[120:121], 0, s[30:31]
	global_store_dword v[224:225], v221, off sc1 nt
	s_waitcnt vmcnt(39)
	v_lshlrev_b32_e32 v224, 16, v180
	v_and_b32_e32 v225, 0xffff0000, v180
	v_pk_add_f32 v[208:209], v[208:209], v[224:225]
	s_nop 0
	v_pk_add_f32 v[208:209], v[208:209], v[222:223]
	s_nop 0
	v_pk_add_f32 v[128:129], v[208:209], v[128:129]
	s_nop 0
	v_pk_add_f32 v[128:129], v[128:129], v[130:131]
	s_nop 0
	v_pk_add_f32 v[128:129], v[128:129], v[132:133]
	s_nop 0
	v_pk_add_f32 v[128:129], v[128:129], v[134:135]
	s_nop 0
	v_pk_add_f32 v[128:129], v[128:129], v[122:123]
	s_nop 0
	v_pk_fma_f32 v[128:129], v[128:129], s[12:13], v[224:225] op_sel_hi:[1,0,1] neg_lo:[0,0,1] neg_hi:[0,0,1]
	s_nop 0
	v_cvt_pk_bf16_f32 v229, v128, v129

; #define PC_POOL(WIN) do { _Pragma("unroll") for (int t = 0; t < 8; ++t) { const f32x2 ut = bf2x2(uraw[15 + t]); f32x2 s = ut; _Pragma("unroll") for (int j = 1; j < WIN; ++j) s += bf2x2(uraw[15 + t - j]); \
;         const int cnt = min(ts + t + 1, WIN); const f32x2 p = s * __builtin_amdgcn_rcpf((float)cnt) - ut; *(unsigned*)(A2 + (size_t)(mt + t) * 1024 + c0) = pk2(p.x, p.y); } } while (0)
; __device__ __forceinline__ void pc_pass(int Q, const bf16* UG, bf16* A2, const float* cw, const float* cbias, LAS float* Yw, int mt, int ts, int lane) {
;     ...
;     if (Q == 0) PC_POOL(2); else if (Q == 1) PC_POOL(4); else if (Q == 2) PC_POOL(8); else PC_POOL(16);
.LBB0_224:
	s_andn2_b64 vcc, exec, s[12:13]
	s_cbranch_vccnz .LBB0_226
	v_lshlrev_b32_e32 v128, 16, v220
	v_and_b32_e32 v129, 0xffff0000, v220
	v_pk_add_f32 v[130:131], v[124:125], v[128:129]
	v_lshlrev_b32_e32 v132, 16, v219
	v_and_b32_e32 v133, 0xffff0000, v219
	v_pk_add_f32 v[130:131], v[130:131], v[132:133]
	s_mov_b32 s12, 0x3e800000
	v_pk_fma_f32 v[130:131], v[32:33], v[130:131], v[122:123] neg_lo:[0,0,1] neg_hi:[0,0,1]
	s_nop 0
	v_cvt_pk_bf16_f32 v132, v130, v131
	v_lshl_add_u64 v[130:131], v[120:121], 0, s[34:35]
	global_store_dword v[130:131], v132, off sc1 nt
	s_waitcnt vmcnt(39)
	v_lshlrev_b32_e32 v130, 16, v190
	v_and_b32_e32 v131, 0xffff0000, v190
	v_pk_add_f32 v[132:133], v[122:123], v[130:131]
	s_nop 0
	v_pk_add_f32 v[132:133], v[132:133], v[126:127]
	s_nop 0
	v_pk_add_f32 v[128:129], v[132:133], v[128:129]
	s_nop 0
	v_pk_fma_f32 v[128:129], v[34:35], v[128:129], v[130:131] neg_lo:[0,0,1] neg_hi:[0,0,1]
	s_nop 0
	v_cvt_pk_bf16_f32 v132, v128, v129
	v_lshl_add_u64 v[128:129], v[120:121], 0, s[76:77]
	global_store_dword v[128:129], v132, off sc1 nt
	s_waitcnt vmcnt(39)
	v_lshlrev_b32_e32 v128, 16, v188
	v_and_b32_e32 v129, 0xffff0000, v188
	v_pk_add_f32 v[132:133], v[130:131], v[128:129]
	s_nop 0
	v_pk_add_f32 v[132:133], v[132:133], v[122:123]
	s_nop 0
	v_pk_add_f32 v[126:127], v[132:133], v[126:127]
	s_nop 0
	v_pk_fma_f32 v[126:127], v[36:37], v[126:127], v[128:129] neg_lo:[0,0,1] neg_hi:[0,0,1]
	s_nop 0
	v_cvt_pk_bf16_f32 v132, v126, v127
	v_lshl_add_u64 v[126:127], v[120:121], 0, s[66:67]
	global_store_dword v[126:127], v132, off sc1 nt
	s_waitcnt vmcnt(39)
	v_lshlrev_b32_e32 v126, 16, v186
	v_and_b32_e32 v127, 0xffff0000, v186
	v_pk_add_f32 v[132:133], v[128:129], v[126:127]
	s_nop 0
	v_pk_add_f32 v[132:133], v[132:133], v[130:131]
	s_nop 0
	v_pk_add_f32 v[132:133], v[132:133], v[122:123]
	s_nop 0
	v_pk_fma_f32 v[132:133], v[132:133], s[12:13], v[126:127] op_sel_hi:[1,0,1] neg_lo:[0,0,1] neg_hi:[0,0,1]
	s_nop 0
	v_cvt_pk_bf16_f32 v134, v132, v133
	v_lshl_add_u64 v[132:133], v[120:121], 0, s[78:79]
	global_store_dword v[132:133], v134, off sc1 nt
	s_waitcnt vmcnt(39)
	v_lshlrev_b32_e32 v132, 16, v184
	v_and_b32_e32 v133, 0xffff0000, v184
	v_pk_add_f32 v[134:135], v[126:127], v[132:133]
	s_nop 0
	v_pk_add_f32 v[134:135], v[134:135], v[128:129]
	s_nop 0
	v_pk_add_f32 v[130:131], v[134:135], v[130:131]
	s_nop 0
	v_pk_fma_f32 v[130:131], v[130:131], s[12:13], v[132:133] op_sel_hi:[1,0,1] neg_lo:[0,0,1] neg_hi:[0,0,1]
	s_nop 0
	v_cvt_pk_bf16_f32 v134, v130, v131
	v_lshl_add_u64 v[130:131], v[120:121], 0, s[70:71]
	global_store_dword v[130:131], v134, off sc1 nt
	s_waitcnt vmcnt(39)
	v_lshlrev_b32_e32 v130, 16, v182
	v_and_b32_e32 v131, 0xffff0000, v182
	v_pk_add_f32 v[134:135], v[132:133], v[130:131]
	s_nop 0
	v_pk_add_f32 v[134:135], v[134:135], v[126:127]
	s_nop 0
	v_pk_add_f32 v[128:129], v[134:135], v[128:129]
	s_nop 0
	v_pk_fma_f32 v[128:129], v[128:129], s[12:13], v[130:131] op_sel_hi:[1,0,1] neg_lo:[0,0,1] neg_hi:[0,0,1]
	s_nop 0
	v_cvt_pk_bf16_f32 v134, v128, v129
	v_lshl_add_u64 v[128:129], v[120:121], 0, s[64:65]
	global_store_dword v[128:129], v134, off sc1 nt
	s_waitcnt vmcnt(39)
	v_lshlrev_b32_e32 v128, 16, v181
	v_and_b32_e32 v129, 0xffff0000, v181
	v_pk_add_f32 v[134:135], v[130:131], v[128:129]
	s_nop 0
	v_pk_add_f32 v[134:135], v[134:135], v[132:133]
	s_nop 0
	v_pk_add_f32 v[126:127], v[134:135], v[126:127]
	s_nop 0
	v_pk_fma_f32 v[126:127], v[126:127], s[12:13], v[128:129] op_sel_hi:[1,0,1] neg_lo:[0,0,1] neg_hi:[0,0,1]
	s_nop 0
	v_cvt_pk_bf16_f32 v134, v126, v127
	v_lshl_add_u64 v[126:127], v[120:121], 0, s[30:31]
	global_store_dword v[126:127], v134, off sc1 nt
	s_waitcnt vmcnt(39)
	v_lshlrev_b32_e32 v126, 16, v180
	v_and_b32_e32 v127, 0xffff0000, v180
	v_pk_add_f32 v[128:129], v[128:129], v[126:127]
	s_nop 0
	v_pk_add_f32 v[128:129], v[128:129], v[130:131]
	s_nop 0
	v_pk_add_f32 v[128:129], v[128:129], v[132:133]
	s_nop 0
	v_pk_fma_f32 v[126:127], v[128:129], s[12:13], v[126:127] op_sel_hi:[1,0,1] neg_lo:[0,0,1] neg_hi:[0,0,1]
	s_nop 0
	v_cvt_pk_bf16_f32 v229, v126, v127

; #define PC_POOL(WIN) do { _Pragma("unroll") for (int t = 0; t < 8; ++t) { const f32x2 ut = bf2x2(uraw[15 + t]); f32x2 s = ut; _Pragma("unroll") for (int j = 1; j < WIN; ++j) s += bf2x2(uraw[15 + t - j]); \
;         const int cnt = min(ts + t + 1, WIN); const f32x2 p = s * __builtin_amdgcn_rcpf((float)cnt) - ut; *(unsigned*)(A2 + (size_t)(mt + t) * 1024 + c0) = pk2(p.x, p.y); } } while (0)
; __device__ __forceinline__ void pc_pass(int Q, const bf16* UG, bf16* A2, const float* cw, const float* cbias, LAS float* Yw, int mt, int ts, int lane) {
;     ...
;     if (Q == 0) PC_POOL(2); else if (Q == 1) PC_POOL(4); else if (Q == 2) PC_POOL(8); else PC_POOL(16);
.LBB0_227:
	s_andn2_b64 vcc, exec, s[12:13]
	s_cbranch_vccnz .LBB0_140
	v_pk_fma_f32 v[124:125], v[38:39], v[124:125], v[122:123] neg_lo:[0,0,1] neg_hi:[0,0,1]
	s_nop 0
	v_cvt_pk_bf16_f32 v126, v124, v125
	v_lshl_add_u64 v[124:125], v[120:121], 0, s[34:35]
	global_store_dword v[124:125], v126, off sc1 nt
	s_waitcnt vmcnt(39)
	v_lshlrev_b32_e32 v124, 16, v190
	v_and_b32_e32 v125, 0xffff0000, v190
	v_pk_add_f32 v[122:123], v[122:123], v[124:125]
	s_nop 0
	v_pk_fma_f32 v[122:123], v[122:123], 0.5, v[124:125] op_sel_hi:[1,0,1] neg_lo:[0,0,1] neg_hi:[0,0,1]
	s_nop 0
	v_cvt_pk_bf16_f32 v126, v122, v123
	v_lshl_add_u64 v[122:123], v[120:121], 0, s[76:77]
	global_store_dword v[122:123], v126, off sc1 nt
	s_waitcnt vmcnt(39)
	v_lshlrev_b32_e32 v122, 16, v188
	v_and_b32_e32 v123, 0xffff0000, v188
	v_pk_add_f32 v[124:125], v[124:125], v[122:123]
	s_nop 0
	v_pk_fma_f32 v[124:125], v[124:125], 0.5, v[122:123] op_sel_hi:[1,0,1] neg_lo:[0,0,1] neg_hi:[0,0,1]
	s_nop 0
	v_cvt_pk_bf16_f32 v126, v124, v125
	v_lshl_add_u64 v[124:125], v[120:121], 0, s[66:67]
	global_store_dword v[124:125], v126, off sc1 nt
	s_waitcnt vmcnt(39)
	v_lshlrev_b32_e32 v124, 16, v186
	v_and_b32_e32 v125, 0xffff0000, v186
	v_pk_add_f32 v[122:123], v[122:123], v[124:125]
	s_nop 0
	v_pk_fma_f32 v[122:123], v[122:123], 0.5, v[124:125] op_sel_hi:[1,0,1] neg_lo:[0,0,1] neg_hi:[0,0,1]
	s_nop 0
	v_cvt_pk_bf16_f32 v126, v122, v123
	v_lshl_add_u64 v[122:123], v[120:121], 0, s[78:79]
	global_store_dword v[122:123], v126, off sc1 nt
	s_waitcnt vmcnt(39)
	v_lshlrev_b32_e32 v122, 16, v184
	v_and_b32_e32 v123, 0xffff0000, v184
	v_pk_add_f32 v[124:125], v[124:125], v[122:123]
	s_nop 0
	v_pk_fma_f32 v[124:125], v[124:125], 0.5, v[122:123] op_sel_hi:[1,0,1] neg_lo:[0,0,1] neg_hi:[0,0,1]
	s_nop 0
	v_cvt_pk_bf16_f32 v126, v124, v125
	v_lshl_add_u64 v[124:125], v[120:121], 0, s[70:71]
	global_store_dword v[124:125], v126, off sc1 nt
	s_waitcnt vmcnt(39)
	v_lshlrev_b32_e32 v124, 16, v182
	v_and_b32_e32 v125, 0xffff0000, v182
	v_pk_add_f32 v[122:123], v[122:123], v[124:125]
	s_nop 0
	v_pk_fma_f32 v[122:123], v[122:123], 0.5, v[124:125] op_sel_hi:[1,0,1] neg_lo:[0,0,1] neg_hi:[0,0,1]
	s_nop 0
	v_cvt_pk_bf16_f32 v126, v122, v123
	v_lshl_add_u64 v[122:123], v[120:121], 0, s[64:65]
	global_store_dword v[122:123], v126, off sc1 nt
	s_waitcnt vmcnt(39)
	v_lshlrev_b32_e32 v122, 16, v181
	v_and_b32_e32 v123, 0xffff0000, v181
	v_pk_add_f32 v[124:125], v[124:125], v[122:123]
	s_nop 0
	v_pk_fma_f32 v[124:125], v[124:125], 0.5, v[122:123] op_sel_hi:[1,0,1] neg_lo:[0,0,1] neg_hi:[0,0,1]
	s_nop 0
	v_cvt_pk_bf16_f32 v126, v124, v125
	v_lshl_add_u64 v[124:125], v[120:121], 0, s[30:31]
	global_store_dword v[124:125], v126, off sc1 nt
	s_waitcnt vmcnt(39)
	v_lshlrev_b32_e32 v124, 16, v180
	v_and_b32_e32 v125, 0xffff0000, v180
	v_pk_add_f32 v[122:123], v[122:123], v[124:125]
	s_nop 0
	v_pk_fma_f32 v[122:123], v[122:123], 0.5, v[124:125] op_sel_hi:[1,0,1] neg_lo:[0,0,1] neg_hi:[0,0,1]
	s_nop 0
	v_cvt_pk_bf16_f32 v229, v122, v123
	s_branch .LBB0_140

; __device__ __forceinline__ float silu_f(float x) { return x * __builtin_amdgcn_rcpf(1.0f + __builtin_amdgcn_exp2f(x * -1.44269504089f)); }
; #define LAS __attribute__((address_space(3)))
; __device__ __forceinline__ unsigned pk2(float lo, float hi) { return pg8::cvt_pk_bf16(lo, hi); }
; __device__ __forceinline__ void poolconv_phase(CArgs* a, LAS unsigned char* lds, int G, int tid, int wave, int lane) {
;     ...
;         for (int t = 0; t < 8; ++t) { const LAS f32x4* yr = (const LAS f32x4*)(Yw + t * 512 + c8); const f32x4 p0 = yr[0], p1 = yr[1];
;             float s1 = (p0[0] + p0[1]) + (p0[2] + p0[3]) + (p1[0] + p1[1]) + (p1[2] + p1[3]);
;             float s2 = (p0[0] * p0[0] + p0[1] * p0[1]) + (p0[2] * p0[2] + p0[3] * p0[3]) + (p1[0] * p1[0] + p1[1] * p1[1]) + (p1[2] * p1[2] + p1[3] * p1[3]);
; #pragma unroll
;             for (int o = 1; o < 64; o <<= 1) { s1 += __shfl_xor(s1, o); s2 += __shfl_xor(s2, o); }
;             const float mean = s1 * (1.f / 512.f), rs = __builtin_amdgcn_rsqf(s2 * (1.f / 512.f) - mean * mean + EPS);
;             const f32x4 v0 = (p0 - mean) * rs * lg0 + lb0, v1 = (p1 - mean) * rs * lg1 + lb1;
;             v4u o; o.x = pk2(pg8::silu_f(v0[0]), pg8::silu_f(v0[1])); o.y = pk2(pg8::silu_f(v0[2]), pg8::silu_f(v0[3])); o.z = pk2(pg8::silu_f(v1[0]), pg8::silu_f(v1[1])); o.w = pk2(pg8::silu_f(v1[2]), pg8::silu_f(v1[3]));
;             *(v4u*)(A2 + (size_t)(mt + t) * 1024 + 512 + c8) = o; }
.LBB0_244:
	v_add_u32_e32 v28, s2, v210
	ds_read_b128 v[16:19], v28
	ds_read_b128 v[30:33], v28 offset:16
	s_ashr_i32 s1, s0, 31
	s_lshl_b64 s[4:5], s[0:1], 11
	s_addk_i32 s2, 0x1000
	s_waitcnt lgkmcnt(1)
	v_mul_f32_e32 v34, v16, v16
	v_mul_f32_e32 v36, v17, v17
	v_mul_f32_e32 v38, v18, v18
	v_mul_f32_e32 v40, v19, v19
	v_mov_b32_e32 v35, v16
	v_mov_b32_e32 v37, v17
	v_mov_b32_e32 v39, v18
	v_mov_b32_e32 v41, v19
	s_waitcnt lgkmcnt(0)
	v_mul_f32_e32 v42, v30, v30
	v_mul_f32_e32 v44, v31, v31
	v_pk_add_f32 v[34:35], v[34:35], v[36:37]
	v_pk_add_f32 v[36:37], v[38:39], v[40:41]
	v_mov_b32_e32 v43, v30
	v_mov_b32_e32 v45, v31
	v_mul_f32_e32 v46, v32, v32
	v_mul_f32_e32 v48, v33, v33
	v_pk_add_f32 v[34:35], v[34:35], v[36:37]
	v_pk_add_f32 v[36:37], v[42:43], v[44:45]
	v_mov_b32_e32 v47, v32
	v_mov_b32_e32 v49, v33
	v_pk_add_f32 v[34:35], v[34:35], v[36:37]
	v_pk_add_f32 v[36:37], v[46:47], v[48:49]
	s_nop 0
	v_pk_add_f32 v[34:35], v[36:37], v[34:35]
	ds_bpermute_b32 v37, v22, v35
	ds_bpermute_b32 v36, v22, v34
	s_waitcnt lgkmcnt(0)
	v_pk_add_f32 v[34:35], v[34:35], v[36:37]
	ds_bpermute_b32 v37, v23, v35
	ds_bpermute_b32 v36, v23, v34
	s_waitcnt lgkmcnt(0)
	v_pk_add_f32 v[34:35], v[34:35], v[36:37]
	ds_bpermute_b32 v37, v24, v35
	ds_bpermute_b32 v36, v24, v34
	s_waitcnt lgkmcnt(0)
	v_pk_add_f32 v[34:35], v[34:35], v[36:37]
	ds_bpermute_b32 v37, v25, v35
	ds_bpermute_b32 v36, v25, v34
	s_waitcnt lgkmcnt(0)
	v_pk_add_f32 v[34:35], v[34:35], v[36:37]
	ds_bpermute_b32 v37, v26, v35
	ds_bpermute_b32 v36, v26, v34
	s_waitcnt lgkmcnt(0)
	v_pk_add_f32 v[34:35], v[34:35], v[36:37]
	ds_bpermute_b32 v37, v27, v35
	ds_bpermute_b32 v36, v27, v34
	s_waitcnt lgkmcnt(0)
	v_pk_add_f32 v[34:35], v[34:35], v[36:37]
	s_nop 0
	v_pk_mul_f32 v[34:35], v[34:35], s[6:7] op_sel_hi:[1,0]
	s_nop 0
	v_fma_f32 v29, -v35, v35, v34
	v_add_f32_e32 v29, 0x358637bd, v29
	v_rsq_f32_e32 v34, v29
	v_sub_f32_e32 v17, v17, v35
	v_sub_f32_e32 v16, v16, v35
	v_sub_f32_e32 v19, v19, v35
	v_pk_mul_f32 v[16:17], v[16:17], v[34:35] op_sel_hi:[1,0]
	v_sub_f32_e32 v18, v18, v35
	v_pk_fma_f32 v[16:17], v[4:5], v[16:17], v[12:13]
	v_pk_mul_f32 v[18:19], v[18:19], v[34:35] op_sel_hi:[1,0]
	v_mul_f32_e32 v29, 0xbfb8aa3b, v16
	v_exp_f32_e32 v29, v29
	v_pk_fma_f32 v[18:19], v[6:7], v[18:19], v[14:15]
	v_sub_f32_e32 v31, v31, v35
	v_sub_f32_e32 v30, v30, v35
	v_add_f32_e32 v29, 1.0, v29
	v_rcp_f32_e32 v29, v29
	v_pk_mul_f32 v[30:31], v[30:31], v[34:35] op_sel_hi:[1,0]
	v_sub_f32_e32 v33, v33, v35
	v_pk_fma_f32 v[30:31], v[0:1], v[30:31], v[8:9]
	v_mul_f32_e32 v16, v16, v29
	v_mul_f32_e32 v29, 0xbfb8aa3b, v17
	v_exp_f32_e32 v29, v29
	v_sub_f32_e32 v32, v32, v35
	v_pk_mul_f32 v[32:33], v[32:33], v[34:35] op_sel_hi:[1,0]
	v_add_f32_e32 v29, 1.0, v29
	v_rcp_f32_e32 v29, v29
	v_pk_fma_f32 v[32:33], v[2:3], v[32:33], v[10:11]
	v_mul_f32_e32 v17, v17, v29
	v_cvt_pk_bf16_f32 v16, v16, v17
	v_mul_f32_e32 v17, 0xbfb8aa3b, v18
	v_exp_f32_e32 v17, v17
	v_mul_f32_e32 v29, 0xbfb8aa3b, v33
	v_exp_f32_e32 v29, v29
	v_add_f32_e32 v17, 1.0, v17
	v_rcp_f32_e32 v17, v17
	v_add_f32_e32 v29, 1.0, v29
	v_rcp_f32_e32 v29, v29
	v_mul_f32_e32 v17, v18, v17
	v_mul_f32_e32 v18, 0xbfb8aa3b, v19
	v_exp_f32_e32 v18, v18
	v_mul_f32_e32 v29, v33, v29
	v_add_f32_e32 v18, 1.0, v18
	v_rcp_f32_e32 v18, v18
	s_nop 0
	v_mul_f32_e32 v18, v19, v18
	v_cvt_pk_bf16_f32 v17, v17, v18
	v_mul_f32_e32 v18, 0xbfb8aa3b, v30
	v_mul_f32_e32 v19, 0xbfb8aa3b, v31
	v_exp_f32_e32 v18, v18
	v_exp_f32_e32 v19, v19
	v_add_f32_e32 v18, 1.0, v18
	v_add_f32_e32 v19, 1.0, v19
	v_rcp_f32_e32 v18, v18
	v_rcp_f32_e32 v19, v19
	v_mul_f32_e32 v18, v30, v18
	v_mul_f32_e32 v19, v31, v19
	v_cvt_pk_bf16_f32 v18, v18, v19
	v_mul_f32_e32 v19, 0xbfb8aa3b, v32
	v_exp_f32_e32 v19, v19
	v_lshl_add_u64 v[30:31], v[20:21], 0, s[4:5]
	s_add_i32 s4, s0, 1
	s_ashr_i32 s5, s4, 31
	v_add_f32_e32 v19, 1.0, v19
	v_rcp_f32_e32 v19, v19
	s_lshl_b64 s[4:5], s[4:5], 11
	s_add_i32 s0, s0, 2
	s_cmpk_eq_i32 s2, 0x4000
	v_mul_f32_e32 v19, v32, v19
	v_cvt_pk_bf16_f32 v19, v19, v29
	global_store_dwordx4 v[30:31], v[16:19], off offset:1024 sc1 nt
	ds_read_b128 v[16:19], v28 offset:2048
	ds_read_b128 v[28:31], v28 offset:2064
	s_waitcnt lgkmcnt(1)
	v_mul_f32_e32 v32, v16, v16
	v_mul_f32_e32 v34, v17, v17
	v_mul_f32_e32 v36, v18, v18
	v_mul_f32_e32 v38, v19, v19
	v_mov_b32_e32 v33, v16
	v_mov_b32_e32 v35, v17
	v_mov_b32_e32 v37, v18
	v_mov_b32_e32 v39, v19
	s_waitcnt lgkmcnt(0)
; __device__ __forceinline__ float silu_f(float x) { return x * __builtin_amdgcn_rcpf(1.0f + __builtin_amdgcn_exp2f(x * -1.44269504089f)); }
; #define LAS __attribute__((address_space(3)))
; __device__ __forceinline__ unsigned pk2(float lo, float hi) { return pg8::cvt_pk_bf16(lo, hi); }
; __device__ __forceinline__ void poolconv_phase(CArgs* a, LAS unsigned char* lds, int G, int tid, int wave, int lane) {
;     ...
;         for (int t = 0; t < 8; ++t) { const LAS f32x4* yr = (const LAS f32x4*)(Yw + t * 512 + c8); const f32x4 p0 = yr[0], p1 = yr[1];
;             float s1 = (p0[0] + p0[1]) + (p0[2] + p0[3]) + (p1[0] + p1[1]) + (p1[2] + p1[3]);
;             float s2 = (p0[0] * p0[0] + p0[1] * p0[1]) + (p0[2] * p0[2] + p0[3] * p0[3]) + (p1[0] * p1[0] + p1[1] * p1[1]) + (p1[2] * p1[2] + p1[3] * p1[3]);
; #pragma unroll
;             for (int o = 1; o < 64; o <<= 1) { s1 += __shfl_xor(s1, o); s2 += __shfl_xor(s2, o); }
;             const float mean = s1 * (1.f / 512.f), rs = __builtin_amdgcn_rsqf(s2 * (1.f / 512.f) - mean * mean + EPS);
;             const f32x4 v0 = (p0 - mean) * rs * lg0 + lb0, v1 = (p1 - mean) * rs * lg1 + lb1;
;             v4u o; o.x = pk2(pg8::silu_f(v0[0]), pg8::silu_f(v0[1])); o.y = pk2(pg8::silu_f(v0[2]), pg8::silu_f(v0[3])); o.z = pk2(pg8::silu_f(v1[0]), pg8::silu_f(v1[1])); o.w = pk2(pg8::silu_f(v1[2]), pg8::silu_f(v1[3]));
;             *(v4u*)(A2 + (size_t)(mt + t) * 1024 + 512 + c8) = o; }
;     }
	v_mul_f32_e32 v40, v28, v28
	v_mul_f32_e32 v42, v29, v29
	v_pk_add_f32 v[32:33], v[32:33], v[34:35]
	v_pk_add_f32 v[34:35], v[36:37], v[38:39]
	v_mov_b32_e32 v41, v28
	v_mov_b32_e32 v43, v29
	v_mul_f32_e32 v44, v30, v30
	v_mul_f32_e32 v46, v31, v31
	v_pk_add_f32 v[32:33], v[32:33], v[34:35]
	v_pk_add_f32 v[34:35], v[40:41], v[42:43]
	v_mov_b32_e32 v45, v30
	v_mov_b32_e32 v47, v31
	v_pk_add_f32 v[32:33], v[32:33], v[34:35]
	v_pk_add_f32 v[34:35], v[44:45], v[46:47]
	s_nop 0
	v_pk_add_f32 v[32:33], v[34:35], v[32:33]
	ds_bpermute_b32 v35, v22, v33
	ds_bpermute_b32 v34, v22, v32
	s_waitcnt lgkmcnt(0)
	v_pk_add_f32 v[32:33], v[32:33], v[34:35]
	ds_bpermute_b32 v35, v23, v33
	ds_bpermute_b32 v34, v23, v32
	s_waitcnt lgkmcnt(0)
	v_pk_add_f32 v[32:33], v[32:33], v[34:35]
	ds_bpermute_b32 v35, v24, v33
	ds_bpermute_b32 v34, v24, v32
	s_waitcnt lgkmcnt(0)
	v_pk_add_f32 v[32:33], v[32:33], v[34:35]
	ds_bpermute_b32 v35, v25, v33
	ds_bpermute_b32 v34, v25, v32
	s_waitcnt lgkmcnt(0)
	v_pk_add_f32 v[32:33], v[32:33], v[34:35]
	ds_bpermute_b32 v35, v26, v33
	ds_bpermute_b32 v34, v26, v32
	s_waitcnt lgkmcnt(0)
	v_pk_add_f32 v[32:33], v[32:33], v[34:35]
	ds_bpermute_b32 v35, v27, v33
	ds_bpermute_b32 v34, v27, v32
	s_waitcnt lgkmcnt(0)
	v_pk_add_f32 v[32:33], v[32:33], v[34:35]
	s_nop 0
	v_pk_mul_f32 v[32:33], v[32:33], s[6:7] op_sel_hi:[1,0]
	s_nop 0
	v_fma_f32 v32, -v33, v33, v32
	v_add_f32_e32 v32, 0x358637bd, v32
	v_rsq_f32_e32 v32, v32
	v_sub_f32_e32 v17, v17, v33
	v_sub_f32_e32 v16, v16, v33
	v_sub_f32_e32 v19, v19, v33
	v_pk_mul_f32 v[16:17], v[16:17], v[32:33] op_sel_hi:[1,0]
	v_sub_f32_e32 v18, v18, v33
	v_pk_fma_f32 v[16:17], v[4:5], v[16:17], v[12:13]
	v_sub_f32_e32 v31, v31, v33
	v_sub_f32_e32 v30, v30, v33
	v_sub_f32_e32 v29, v29, v33
	v_sub_f32_e32 v28, v28, v33
	v_pk_mul_f32 v[18:19], v[18:19], v[32:33] op_sel_hi:[1,0]
	v_pk_mul_f32 v[28:29], v[28:29], v[32:33] op_sel_hi:[1,0]
	v_pk_mul_f32 v[30:31], v[30:31], v[32:33] op_sel_hi:[1,0]
	v_mul_f32_e32 v32, 0xbfb8aa3b, v16
	v_exp_f32_e32 v32, v32
	v_pk_fma_f32 v[18:19], v[6:7], v[18:19], v[14:15]
	v_pk_fma_f32 v[28:29], v[0:1], v[28:29], v[8:9]
	v_pk_fma_f32 v[30:31], v[2:3], v[30:31], v[10:11]
	v_add_f32_e32 v32, 1.0, v32
	v_rcp_f32_e32 v32, v32
	s_nop 0
	v_mul_f32_e32 v16, v16, v32
	v_mul_f32_e32 v32, 0xbfb8aa3b, v17
	v_exp_f32_e32 v32, v32
	s_nop 0
	v_add_f32_e32 v32, 1.0, v32
	v_rcp_f32_e32 v32, v32
	s_nop 0
	v_mul_f32_e32 v17, v17, v32
	v_cvt_pk_bf16_f32 v16, v16, v17
	v_mul_f32_e32 v17, 0xbfb8aa3b, v18
	v_exp_f32_e32 v17, v17
	s_nop 0
	v_add_f32_e32 v17, 1.0, v17
	v_rcp_f32_e32 v17, v17
	s_nop 0
	v_mul_f32_e32 v17, v18, v17
	v_mul_f32_e32 v18, 0xbfb8aa3b, v19
	v_exp_f32_e32 v18, v18
	s_nop 0
	v_add_f32_e32 v18, 1.0, v18
	v_rcp_f32_e32 v18, v18
	s_nop 0
	v_mul_f32_e32 v18, v19, v18
	v_cvt_pk_bf16_f32 v17, v17, v18
	v_mul_f32_e32 v18, 0xbfb8aa3b, v28
	v_mul_f32_e32 v19, 0xbfb8aa3b, v29
	v_exp_f32_e32 v18, v18
	v_exp_f32_e32 v19, v19
	v_add_f32_e32 v18, 1.0, v18
	v_add_f32_e32 v19, 1.0, v19
	v_rcp_f32_e32 v18, v18
	v_rcp_f32_e32 v19, v19
	v_mul_f32_e32 v18, v28, v18
	v_mul_f32_e32 v19, v29, v19
	v_cvt_pk_bf16_f32 v18, v18, v19
	v_mul_f32_e32 v19, 0xbfb8aa3b, v30
	v_mul_f32_e32 v28, 0xbfb8aa3b, v31
	v_exp_f32_e32 v19, v19
	v_exp_f32_e32 v28, v28
	v_add_f32_e32 v19, 1.0, v19
	v_add_f32_e32 v28, 1.0, v28
	v_rcp_f32_e32 v19, v19
	v_rcp_f32_e32 v28, v28
	v_mul_f32_e32 v19, v30, v19
	v_mul_f32_e32 v28, v31, v28
	v_cvt_pk_bf16_f32 v19, v19, v28
	v_lshl_add_u64 v[28:29], v[20:21], 0, s[4:5]
	global_store_dwordx4 v[28:29], v[16:19], off offset:1024 sc1 nt
	s_cbranch_scc0 .LBB0_244
	v_readlane_b32 s62, v252, 4
	v_readlane_b32 s1, v253, 34
	v_readlane_b32 s0, v252, 55
	s_add_i32 s1, s1, s62
	s_add_i32 s3, s3, s0
	s_cmpk_gt_i32 s1, 0x1ff
	v_readlane_b32 s63, v252, 5
	s_cbranch_scc0 .LBB0_139
	v_readlane_b32 s92, v252, 57
	v_readlane_b32 s96, v252, 59
	v_readlane_b32 s60, v252, 0
	v_readlane_b32 s64, v252, 2
	v_readlane_b32 s66, v252, 61
	v_readlane_b32 s72, v253, 1
	v_readlane_b32 s74, v253, 3
	v_readlane_b32 s80, v253, 5
	v_readlane_b32 s82, v253, 7
	v_readlane_b32 s84, v253, 9
	v_readlane_b32 s88, v253, 21
	v_readlane_b32 s90, v253, 11
	v_readlane_b32 s78, v253, 17
	v_readlane_b32 s50, v253, 15
	v_readlane_b32 s93, v252, 58
	v_readlane_b32 s97, v252, 60
	v_readlane_b32 s61, v252, 1
	v_readlane_b32 s65, v252, 3
	v_readlane_b32 s67, v252, 62
	v_readlane_b32 s68, v252, 63
	v_readlane_b32 s69, v253, 0
	s_movk_i32 s70, 0xb00
	v_readlane_b32 s73, v253, 2
	v_readlane_b32 s75, v253, 4
	v_readlane_b32 s81, v253, 6
	v_readlane_b32 s83, v253, 8
	v_readlane_b32 s85, v253, 10
	v_readlane_b32 s89, v253, 22
	v_readlane_b32 s91, v253, 12
	v_readlane_b32 s63, v253, 13
	s_movk_i32 s71, 0x161
	v_readlane_b32 s47, v252, 56
	s_mov_b64 s[26:27], 0xb00
	v_readlane_b32 s25, v253, 20
	s_movk_i32 s59, 0x1600
	s_mov_b64 s[30:31], 0x200
	s_mov_b32 s87, 0x40000
	s_mov_b64 s[34:35], 0x8000
	v_readlane_b32 s76, v253, 19
	v_readlane_b32 s79, v253, 18
	v_readlane_b32 s51, v253, 16
	v_readlane_b32 s2, v253, 14

; __device__ __forceinline__ unsigned pk2(float lo, float hi) { return pg8::cvt_pk_bf16(lo, hi); }
; __device__ __forceinline__ void sgu_phase(CArgs* a, LAS unsigned char* lds, int G, int tid, int wave, int lane) {
;     ...
; #pragma unroll
;             for (int cbk = 0; cbk < 8; ++cbk) { const int col = h * 128 + 16 * cbk + 4 * fq;
;                 const float u0 = __builtin_bit_cast(float, uu[cbk].x << 16), u1 = __builtin_bit_cast(float, uu[cbk].x & 0xffff0000u), u2 = __builtin_bit_cast(float, uu[cbk].y << 16), u3 = __builtin_bit_cast(float, uu[cbk].y & 0xffff0000u);
;                 v2u o; o.x = pk2(u0 * (acc[cbk][0] + bs), u1 * (acc[cbk][1] + bs)); o.y = pk2(u2 * (acc[cbk][2] + bs), u3 * (acc[cbk][3] + bs));
;                 *(v2u*)(A3 + row * 1024 + col) = o; }
;             __syncthreads();
.LBB0_947:
	s_waitcnt vmcnt(7)
	v_lshlrev_b32_e32 v79, 16, v122
	v_and_b32_e32 v83, 0xffff0000, v122
	v_add_f32_e32 v56, v71, v56
	v_add_f32_e32 v57, v71, v57
	v_mul_f32_e32 v56, v56, v79
	v_mul_f32_e32 v57, v57, v83
	v_lshlrev_b32_e32 v85, 16, v123
	v_and_b32_e32 v87, 0xffff0000, v123
	v_cvt_pk_bf16_f32 v56, v56, v57
	v_add_f32_e32 v57, v71, v58
	v_add_f32_e32 v58, v71, v59
	v_mul_f32_e32 v57, v57, v85
	v_mul_f32_e32 v58, v58, v87
	v_cvt_pk_bf16_f32 v57, v57, v58
	v_lshl_add_u64 v[58:59], v[90:91], 0, s[2:3]
	global_store_dwordx2 v[58:59], v[56:57], off offset:-128 sc1 nt
	s_waitcnt vmcnt(7)
	v_lshlrev_b32_e32 v56, 16, v120
	v_and_b32_e32 v57, 0xffff0000, v120
	v_add_f32_e32 v52, v71, v52
	v_add_f32_e32 v53, v71, v53
	v_mul_f32_e32 v52, v52, v56
	v_mul_f32_e32 v53, v53, v57
	v_lshlrev_b32_e32 v79, 16, v121
	v_cvt_pk_bf16_f32 v52, v52, v53
	v_add_f32_e32 v53, v71, v54
	v_and_b32_e32 v83, 0xffff0000, v121
	v_mul_f32_e32 v53, v53, v79
	v_add_f32_e32 v54, v71, v55
	v_mul_f32_e32 v54, v54, v83
	v_cvt_pk_bf16_f32 v53, v53, v54
	global_store_dwordx2 v[58:59], v[52:53], off offset:-96 sc1 nt
	s_waitcnt vmcnt(7)
	v_lshlrev_b32_e32 v52, 16, v118
	v_and_b32_e32 v53, 0xffff0000, v118
	v_add_f32_e32 v44, v71, v44
	v_add_f32_e32 v45, v71, v45
	v_mul_f32_e32 v44, v44, v52
	v_mul_f32_e32 v45, v45, v53
	v_lshlrev_b32_e32 v54, 16, v119
	v_cvt_pk_bf16_f32 v44, v44, v45
	v_add_f32_e32 v45, v71, v46
	v_and_b32_e32 v55, 0xffff0000, v119
	v_mul_f32_e32 v45, v45, v54
	v_add_f32_e32 v46, v71, v47
	v_mul_f32_e32 v46, v46, v55
	v_cvt_pk_bf16_f32 v45, v45, v46
	global_store_dwordx2 v[58:59], v[44:45], off offset:-64 sc1 nt
	s_waitcnt vmcnt(7)
	v_lshlrev_b32_e32 v44, 16, v116
	v_and_b32_e32 v45, 0xffff0000, v116
	v_add_f32_e32 v40, v71, v40
	v_add_f32_e32 v41, v71, v41
	v_mul_f32_e32 v40, v40, v44
	v_mul_f32_e32 v41, v41, v45
	v_lshlrev_b32_e32 v46, 16, v117
	v_cvt_pk_bf16_f32 v40, v40, v41
	v_add_f32_e32 v41, v71, v42
	v_and_b32_e32 v47, 0xffff0000, v117
	v_mul_f32_e32 v41, v41, v46
	v_add_f32_e32 v42, v71, v43
	v_mul_f32_e32 v42, v42, v47
	v_cvt_pk_bf16_f32 v41, v41, v42
	global_store_dwordx2 v[58:59], v[40:41], off offset:-32 sc1 nt
	s_waitcnt vmcnt(7)
	v_lshlrev_b32_e32 v40, 16, v114
	v_add_f32_e32 v44, v71, v48
	v_and_b32_e32 v41, 0xffff0000, v114
	v_mul_f32_e32 v40, v44, v40
	v_add_f32_e32 v44, v71, v49
	v_mul_f32_e32 v41, v44, v41
	v_lshlrev_b32_e32 v42, 16, v115
	v_cvt_pk_bf16_f32 v40, v40, v41
	v_add_f32_e32 v41, v71, v50
	v_and_b32_e32 v43, 0xffff0000, v115
	v_mul_f32_e32 v41, v41, v42
	v_add_f32_e32 v42, v71, v51
	v_mul_f32_e32 v42, v42, v43
	v_cvt_pk_bf16_f32 v41, v41, v42
	global_store_dwordx2 v[58:59], v[40:41], off sc1 nt
	s_waitcnt vmcnt(7)
	v_lshlrev_b32_e32 v40, 16, v112
	v_and_b32_e32 v41, 0xffff0000, v112
	v_add_f32_e32 v36, v71, v36
	v_add_f32_e32 v37, v71, v37
	v_mul_f32_e32 v36, v36, v40
	v_mul_f32_e32 v37, v37, v41
	v_lshlrev_b32_e32 v42, 16, v113
	v_cvt_pk_bf16_f32 v36, v36, v37
	v_add_f32_e32 v37, v71, v38
	v_and_b32_e32 v43, 0xffff0000, v113
	v_mul_f32_e32 v37, v37, v42
	v_add_f32_e32 v38, v71, v39
	v_mul_f32_e32 v38, v38, v43
	v_cvt_pk_bf16_f32 v37, v37, v38
	global_store_dwordx2 v[58:59], v[36:37], off offset:32 sc1 nt
	s_waitcnt vmcnt(7)
	v_lshlrev_b32_e32 v36, 16, v110
	v_and_b32_e32 v37, 0xffff0000, v110
	v_add_f32_e32 v32, v71, v32
	v_add_f32_e32 v33, v71, v33
	v_mul_f32_e32 v32, v32, v36
	v_mul_f32_e32 v33, v33, v37
	v_lshlrev_b32_e32 v38, 16, v111
	v_cvt_pk_bf16_f32 v32, v32, v33
	v_add_f32_e32 v33, v71, v34
	v_and_b32_e32 v39, 0xffff0000, v111
	v_mul_f32_e32 v33, v33, v38
	v_add_f32_e32 v34, v71, v35
	v_mul_f32_e32 v34, v34, v39
	v_cvt_pk_bf16_f32 v33, v33, v34
	global_store_dwordx2 v[58:59], v[32:33], off offset:64 sc1 nt
	s_waitcnt vmcnt(7)
	v_lshlrev_b32_e32 v32, 16, v108
	v_and_b32_e32 v33, 0xffff0000, v108
	v_add_f32_e32 v28, v71, v28
	v_add_f32_e32 v29, v71, v29
	v_mul_f32_e32 v28, v28, v32
	v_mul_f32_e32 v29, v29, v33
	s_add_u32 s2, s2, 0x100
	v_lshlrev_b32_e32 v34, 16, v109
	v_cvt_pk_bf16_f32 v28, v28, v29
	v_add_f32_e32 v29, v71, v30
	s_addc_u32 s3, s3, 0
	v_and_b32_e32 v35, 0xffff0000, v109
	v_mul_f32_e32 v29, v29, v34
	v_add_f32_e32 v30, v71, v31
	v_lshl_add_u64 v[106:107], v[106:107], 0, s[30:31]
	v_lshl_add_u64 v[104:105], v[104:105], 0, s[30:31]
	v_lshl_add_u64 v[102:103], v[102:103], 0, s[34:35]
	s_cmpk_eq_i32 s2, 0x800
	v_lshl_add_u64 v[100:101], v[100:101], 0, s[30:31]
	v_mul_f32_e32 v30, v30, v35
	v_cvt_pk_bf16_f32 v29, v29, v30
	global_store_dwordx2 v[58:59], v[28:29], off offset:96 sc1 nt
	s_barrier
	s_cbranch_scc1 .LBB0_943
